# V0T fragment-contiguous: phase-1 V epilogue staged through LDS and stored as 16B contiguous pieces; scan phases read contiguous V fragments
# speedup vs baseline: 1.0699x; 1.0068x over previous
.LBB0_202:
	s_lshr_b32 s30, s23, 6
	s_lshl_b32 s30, s30, 19
	s_bfe_u32 s31, s23, 0x20004
	s_lshl_b32 s31, s31, 22
	s_or_b32 s30, s30, s31
	s_lshr_b32 s32, s23, 6
	s_lshl_b32 s32, s32, 20
	s_bfe_u32 s31, s23, 0x20004
	s_lshl_b32 s31, s31, 23
	s_or_b32 s32, s32, s31
	s_and_b32 s31, s23, 15
	s_lshl_b32 s31, s31, 12
	s_or_b32 s32, s32, s31
	s_lshr_b32 s6, s23, 4
	v_lshlrev_b32_e32 v34, 14, v200
	s_and_b32 s6, s6, 3
	v_lshl_or_b32 v34, s3, 23, v34
	s_lshl_b32 s3, s23, 5
	s_lshl_b32 s66, s6, 9
	s_and_b32 s24, s3, 0x1e0
	s_or_b32 s3, s24, s66
	s_lshl_b32 s18, s2, 4
	s_lshl_b32 s2, s2, 10
	v_or_b32_e32 v42, s3, v200
	s_ashr_i32 s19, s18, 31
	s_ashr_i32 s3, s2, 31
	s_lshl_b32 s25, s6, 10
	s_lshl_b32 s28, s5, 6
	v_add_u32_e32 v32, s4, v201
	s_lshl_b32 s4, s6, 13
	v_lshl_or_b32 v34, s5, 19, v34
	v_lshl_add_u32 v36, s6, 8, v201
	s_mov_b32 s5, s67
	s_lshl_b64 s[16:17], s[18:19], 17
	s_lshl_b64 s[6:7], s[18:19], 15
	s_lshl_b64 s[8:9], s[2:3], 1
	s_lshl_b64 s[2:3], s[18:19], 18
	s_lshl_b64 s[18:19], s[18:19], 12
	v_lshl_add_u64 v[40:41], v[158:159], 0, s[4:5]
	s_add_u32 s5, s20, s18
	v_lshl_add_u64 v[38:39], v[156:157], 0, s[66:67]
	s_addc_u32 s27, s21, s19
	v_lshl_add_u64 v[38:39], v[38:39], 0, s[16:17]
	s_add_u32 s26, s5, s25
	s_mov_b32 s5, 0x10000
	v_ashrrev_i32_e32 v37, 31, v36
	v_lshl_add_u64 v[40:41], v[40:41], 0, s[6:7]
	v_lshrrev_b32_e32 v214, 6, v152
	v_and_b32_e32 v215, 63, v152
	v_lshlrev_b32_e32 v214, 13, v214
	v_lshl_or_b32 v214, v215, 4, v214
	v_add_u32_e32 v194, s30, v214
	v_mov_b32_e32 v195, 0
	v_lshl_add_u64 v[38:39], s[0:1], 0, v[194:195]
	v_add_co_u32_e32 v38, vcc, 0xe801000, v38
	s_nop 1
	v_addc_co_u32_e32 v39, vcc, 0, v39, vcc
	global_load_dwordx4 v[96:99], v[38:39], off offset:-4096
	global_load_dwordx4 v[88:91], v[38:39], off offset:-3072
	global_load_dwordx4 v[80:83], v[38:39], off offset:-2048
	global_load_dwordx4 v[72:75], v[38:39], off offset:-1024
	global_load_dwordx4 v[64:67], v[40:41], off
	v_lshlrev_b64 v[36:37], 14, v[36:37]
	v_lshlrev_b32_e32 v42, 14, v42
	v_mov_b32_e32 v43, v187
	v_lshl_add_u64 v[36:37], v[162:163], 0, v[36:37]
	global_load_dwordx4 v[100:103], v[38:39], off
	global_load_dwordx4 v[92:95], v[38:39], off offset:1024
	global_load_dwordx4 v[84:87], v[38:39], off offset:2048
	global_load_dwordx4 v[76:79], v[38:39], off offset:3072
	v_add_co_u32_e32 v38, vcc, s29, v40
	v_lshl_add_u64 v[42:43], v[160:161], 0, v[42:43]
	s_nop 0
	v_addc_co_u32_e32 v39, vcc, 0, v41, vcc
	v_lshl_add_u64 v[36:37], v[36:37], 0, s[8:9]
	v_lshlrev_b32_e32 v218, 4, v215
	v_add_u32_e32 v218, s32, v218
	v_mov_b32_e32 v219, 0
	v_lshl_add_u64 v[42:43], s[0:1], 0, v[218:219]
	v_add_co_u32_e32 v42, vcc, 0x8000000, v42
	s_nop 1
	v_addc_co_u32_e32 v43, vcc, 0, v43, vcc
	global_load_dwordx4 v[68:71], v[38:39], off
	global_load_dwordx4 v[108:111], v[42:43], off
	global_load_dwordx4 v[104:107], v[42:43], off offset:1024
	global_load_dwordx4 v[112:115], v[42:43], off offset:2048
	global_load_dwordx4 v[116:119], v[42:43], off offset:3072
	v_lshrrev_b32_e32 v214, 6, v152
	v_and_b32_e32 v215, 63, v152
	v_lshlrev_b32_e32 v214, 13, v214
	v_lshl_or_b32 v214, v215, 4, v214
	v_add_u32_e32 v194, s30, v214
	v_mov_b32_e32 v195, 0
	v_lshl_add_u64 v[36:37], s[0:1], 0, v[194:195]
	v_add_co_u32_e32 v36, vcc, 0xd001000, v36
	s_nop 1
	v_addc_co_u32_e32 v37, vcc, 0, v37, vcc
	global_load_dwordx4 v[148:151], v[36:37], off offset:-4096
	global_load_dwordx4 v[144:147], v[36:37], off offset:-3072
	global_load_dwordx4 v[140:143], v[36:37], off offset:-2048
	global_load_dwordx4 v[136:139], v[36:37], off offset:-1024
	s_addc_u32 s27, s27, 0
	s_nop 0
	global_load_dwordx4 v[132:135], v[36:37], off
	global_load_dwordx4 v[128:131], v[36:37], off offset:1024
	global_load_dwordx4 v[124:127], v[36:37], off offset:2048
	global_load_dwordx4 v[120:123], v[36:37], off offset:3072
	v_lshl_add_u64 v[36:37], v[152:153], 2, s[26:27]
	s_barrier
	global_load_dword v36, v[36:37], off
	v_ashrrev_i32_e32 v33, 31, v32
	v_lshlrev_b64 v[32:33], 14, v[32:33]
	s_or_b32 s18, s18, s25
	v_mov_b32_e32 v35, v187
	v_lshl_add_u64 v[180:181], s[18:19], 0, v[170:171]
	s_or_b32 s18, s28, s25
	v_or_b32_e32 v32, v154, v32
	s_or_b32 s18, s2, s18
	s_mov_b32 s19, s3
	s_or_b32 s16, s16, s66
	s_or_b32 s6, s6, s4
	v_lshl_add_u64 v[32:33], v[178:179], 0, v[34:35]
	s_mov_b32 s5, 0
	v_lshl_add_u64 v[182:183], s[18:19], 0, v[172:173]
	v_lshl_add_u64 v[192:193], s[16:17], 0, v[174:175]
	v_lshl_add_u64 v[196:197], s[6:7], 0, v[176:177]
	v_add_u32_e32 v198, 0x8010000, v218
	v_mov_b32_e32 v199, 0
	s_mov_b64 s[30:31], 0x10000
	s_waitcnt vmcnt(0)
	ds_write_b32 v155, v36 offset:32768
	s_waitcnt lgkmcnt(0)
	s_barrier
.LBB0_203:
	v_lshl_add_u64 v[32:33], s[0:1], 0, v[180:181]
	global_load_dword v205, v[32:33], off
	v_cvt_pk_bf16_f32 v32, v16, v17
	v_cvt_pk_bf16_f32 v33, v18, v19
	v_cvt_pk_bf16_f32 v34, v20, v21
	v_cvt_pk_bf16_f32 v35, v22, v23
	s_mov_b32 s4, 0xc020000
	s_waitcnt vmcnt(10)
	v_cndmask_b32_e64 v206, v119, v115, s[14:15]
	v_mfma_f32_32x32x16_bf16 v[48:63], v[96:99], v[32:35], 0
	v_cvt_pk_bf16_f32 v96, v24, v25
	v_cvt_pk_bf16_f32 v97, v26, v27
	v_cvt_pk_bf16_f32 v98, v28, v29
	v_cvt_pk_bf16_f32 v99, v30, v31
	v_cndmask_b32_e64 v207, v118, v114, s[14:15]
	v_cndmask_b32_e64 v208, v117, v113, s[14:15]
	v_cndmask_b32_e64 v209, v116, v112, s[14:15]
	v_mfma_f32_32x32x16_bf16 v[48:63], v[88:91], v[96:99], v[48:63]
	v_cvt_pk_bf16_f32 v88, v0, v1
	v_cvt_pk_bf16_f32 v89, v2, v3
	v_cvt_pk_bf16_f32 v90, v4, v5
	v_cvt_pk_bf16_f32 v91, v6, v7
	v_cndmask_b32_e64 v210, v209, v104, s[12:13]
	v_cndmask_b32_e64 v211, v208, v105, s[12:13]
	v_cndmask_b32_e64 v207, v207, v106, s[12:13]
	v_mfma_f32_32x32x16_bf16 v[32:47], v[100:103], v[32:35], 0
	v_cndmask_b32_e64 v206, v206, v107, s[12:13]
	v_cndmask_b32_e64 v209, v206, v111, s[10:11]
	v_cndmask_b32_e64 v208, v207, v110, s[10:11]
	v_cndmask_b32_e64 v207, v211, v109, s[10:11]
	v_cndmask_b32_e64 v206, v210, v108, s[10:11]
	v_add_u32_e32 v210, 0x1800, v204
	v_add_u32_e32 v211, 0x1c00, v204
	v_mfma_f32_32x32x16_bf16 v[48:63], v[80:83], v[88:91], v[48:63]
	v_cvt_pk_bf16_f32 v80, v8, v9
	v_cvt_pk_bf16_f32 v81, v10, v11
	v_cvt_pk_bf16_f32 v82, v12, v13
	v_cvt_pk_bf16_f32 v83, v14, v15
	s_mov_b64 s[6:7], 0x8000
	v_lshl_add_u64 v[180:181], v[180:181], 0, s[86:87]
	s_waitcnt vmcnt(2)
	v_mfma_f32_32x32x16_bf16 v[16:31], v[148:151], v[108:111], v[16:31]
	v_mfma_f32_32x32x16_bf16 v[0:15], v[132:135], v[108:111], v[0:15]
	v_mfma_f32_32x32x16_bf16 v[32:47], v[92:95], v[96:99], v[32:47]
	v_mfma_f32_32x32x16_bf16 v[16:31], v[144:147], v[104:107], v[16:31]
	v_mfma_f32_32x32x16_bf16 v[0:15], v[128:131], v[104:107], v[0:15]
	v_mfma_f32_32x32x16_bf16 v[32:47], v[84:87], v[88:91], v[32:47]
	v_mfma_f32_32x32x16_bf16 v[48:63], v[72:75], v[80:83], v[48:63]
	v_mfma_f32_32x32x16_bf16 v[16:31], v[140:143], v[112:115], v[16:31]
	v_mfma_f32_32x32x16_bf16 v[0:15], v[124:127], v[112:115], v[0:15]
	v_mfma_f32_32x32x16_bf16 v[32:47], v[76:79], v[80:83], v[32:47]
	v_lshl_add_u64 v[76:77], s[0:1], 0, v[194:195]
	v_add_co_u32_e32 v216, vcc, 0xe809000, v76
	s_mov_b32 s4, 0xc030000
	s_nop 0
	v_addc_co_u32_e32 v217, vcc, 0, v77, vcc
	v_mfma_f32_32x32x16_bf16 v[48:63], v[64:67], v[206:209], v[48:63]
	v_lshl_add_u64 v[64:65], s[0:1], 0, v[196:197]
	s_mov_b32 s4, 0xe009000
	global_load_dwordx4 v[96:99], v[216:217], off offset:-4096
	global_load_dwordx4 v[88:91], v[216:217], off offset:-3072
	global_load_dwordx4 v[80:83], v[216:217], off offset:-2048
	global_load_dwordx4 v[72:75], v[216:217], off offset:-1024
	global_load_dwordx4 v[100:103], v[216:217], off
	global_load_dwordx4 v[92:95], v[216:217], off offset:1024
	global_load_dwordx4 v[84:87], v[216:217], off offset:2048
	global_load_dwordx4 v[76:79], v[216:217], off offset:3072
	v_lshl_add_u64 v[192:193], v[192:193], 0, s[58:59]
	v_mfma_f32_32x32x16_bf16 v[16:31], v[136:139], v[116:119], v[16:31]
	v_lshl_add_u64 v[196:197], v[196:197], 0, s[6:7]
	v_mfma_f32_32x32x16_bf16 v[0:15], v[120:123], v[116:119], v[0:15]
	v_lshl_add_u64 v[116:117], s[0:1], 0, v[198:199]
	v_lshl_add_u64 v[198:199], v[198:199], 0, s[30:31]
	v_mfma_f32_32x32x16_bf16 v[32:47], v[68:71], v[206:209], v[32:47]
	v_add_co_u32_e32 v68, vcc, s4, v64
	s_and_b32 s4, s5, 0x100
	s_nop 0
	v_addc_co_u32_e32 v69, vcc, 0, v65, vcc
	v_lshl_add_u32 v206, s4, 2, v202
	global_load_dwordx4 v[64:67], v[68:69], off offset:-4096
	s_nop 0
	global_load_dwordx4 v[68:71], v[68:69], off
	ds_read_b128 v[136:139], v206 offset:32768
	ds_read_b128 v[140:143], v206 offset:32800
	ds_read_b128 v[104:107], v206 offset:32896
	s_mov_b32 s4, 0xd080000
	s_addk_i32 s5, 0x100
	s_waitcnt lgkmcnt(2)
	v_pk_mul_f32 v[16:17], v[16:17], v[136:137]
	v_pk_mul_f32 v[18:19], v[18:19], v[138:139]
	ds_read_b128 v[136:139], v206 offset:32832
	s_waitcnt lgkmcnt(1)
	v_pk_mul_f32 v[0:1], v[0:1], v[104:105]
	v_pk_mul_f32 v[2:3], v[2:3], v[106:107]
	ds_read_b128 v[104:107], v206 offset:32928
	v_pk_mul_f32 v[20:21], v[20:21], v[140:141]
	s_waitcnt lgkmcnt(1)
	v_pk_mul_f32 v[24:25], v[24:25], v[136:137]
	v_pk_mul_f32 v[26:27], v[26:27], v[138:139]
	ds_read_b128 v[136:139], v206 offset:32864
	s_waitcnt lgkmcnt(1)
	v_pk_mul_f32 v[4:5], v[4:5], v[104:105]
	v_pk_mul_f32 v[6:7], v[6:7], v[106:107]
	ds_read_b128 v[104:107], v206 offset:32960
	v_pk_mul_f32 v[22:23], v[22:23], v[142:143]
	s_waitcnt lgkmcnt(1)
	v_pk_mul_f32 v[28:29], v[28:29], v[136:137]
	v_lshl_add_u64 v[136:137], s[0:1], 0, v[194:195]
	v_add_co_u32_e32 v212, vcc, 0xd009000, v136
	s_waitcnt lgkmcnt(0)
	v_pk_mul_f32 v[8:9], v[8:9], v[104:105]
	v_pk_mul_f32 v[10:11], v[10:11], v[106:107]
	ds_read_b128 v[104:107], v206 offset:32992
	v_addc_co_u32_e32 v213, vcc, 0, v137, vcc
	v_pk_mul_f32 v[30:31], v[30:31], v[138:139]
	s_nop 0
	s_waitcnt lgkmcnt(0)
	v_pk_mul_f32 v[12:13], v[12:13], v[104:105]
	v_pk_mul_f32 v[14:15], v[14:15], v[106:107]
	global_load_dwordx4 v[108:111], v[116:117], off
	global_load_dwordx4 v[104:107], v[116:117], off offset:1024
	global_load_dwordx4 v[112:115], v[116:117], off offset:2048
	s_nop 0
	global_load_dwordx4 v[116:119], v[116:117], off offset:3072
	s_nop 0
	global_load_dwordx4 v[120:123], v[212:213], off offset:3072
	global_load_dwordx4 v[124:127], v[212:213], off offset:2048
	global_load_dwordx4 v[128:131], v[212:213], off offset:1024
	global_load_dwordx4 v[132:135], v[212:213], off
	global_load_dwordx4 v[136:139], v[212:213], off offset:-1024
	global_load_dwordx4 v[140:143], v[212:213], off offset:-2048
	global_load_dwordx4 v[144:147], v[212:213], off offset:-3072
	global_load_dwordx4 v[148:151], v[212:213], off offset:-4096
	s_and_b32 s4, s5, 0x100
	v_lshl_add_u32 v206, s4, 2, v155
	s_waitcnt vmcnt(22)
	ds_write_b32 v206, v205 offset:32768
	ds_write2_b32 v204, v48, v49 offset1:32
	ds_write2_b32 v204, v50, v51 offset0:64 offset1:96
	v_add_u32_e32 v205, 0x400, v204
	v_add_u32_e32 v206, 0x800, v204
	v_add_u32_e32 v207, 0xc00, v204
	v_add_u32_e32 v208, 0x1000, v204
	v_add_u32_e32 v209, 0x1400, v204
	ds_write2_b32 v205, v52, v53 offset1:32
	ds_write2_b32 v205, v54, v55 offset0:64 offset1:96
	ds_write2_b32 v206, v56, v57 offset1:32
	ds_write2_b32 v206, v58, v59 offset0:64 offset1:96
	ds_write2_b32 v207, v60, v61 offset1:32
	ds_write2_b32 v207, v62, v63 offset0:64 offset1:96
	ds_write2_b32 v208, v32, v33 offset1:32
	ds_write2_b32 v208, v34, v35 offset0:64 offset1:96
	ds_write2_b32 v209, v36, v37 offset1:32
	ds_write2_b32 v209, v38, v39 offset0:64 offset1:96
	ds_write2_b32 v210, v40, v41 offset1:32
	ds_write2_b32 v210, v42, v43 offset0:64 offset1:96
	ds_write2_b32 v211, v44, v45 offset1:32
	ds_write2_b32 v211, v46, v47 offset0:64 offset1:96
	s_waitcnt lgkmcnt(0)
	s_barrier
	ds_read_b128 v[32:35], v203
	ds_read_b128 v[36:39], v203 offset:16
	ds_read_b128 v[40:43], v203 offset:8192
	ds_read_b128 v[44:47], v203 offset:16384
	ds_read_b128 v[48:51], v203 offset:24576
	v_lshl_add_u64 v[194:195], v[194:195], 0, s[6:7]
	s_cmpk_eq_i32 s5, 0xf00
	s_waitcnt lgkmcnt(2)
	v_pk_add_f32 v[32:33], v[32:33], v[40:41]
	s_waitcnt lgkmcnt(1)
	v_pk_add_f32 v[32:33], v[32:33], v[44:45]
	s_waitcnt lgkmcnt(0)
	v_pk_add_f32 v[48:49], v[32:33], v[48:49]
	v_pk_add_f32 v[32:33], v[34:35], v[42:43]
	ds_read_b128 v[40:43], v203 offset:16400
	v_pk_add_f32 v[32:33], v[32:33], v[46:47]
	ds_read_b128 v[44:47], v203 offset:24592
	v_pk_add_f32 v[50:51], v[32:33], v[50:51]
	ds_read_b128 v[32:35], v203 offset:8208
	s_waitcnt lgkmcnt(0)
	v_pk_add_f32 v[32:33], v[36:37], v[32:33]
	s_nop 0
	v_pk_add_f32 v[32:33], v[32:33], v[40:41]
	s_nop 0
	v_pk_add_f32 v[36:37], v[32:33], v[44:45]
	v_pk_add_f32 v[32:33], v[38:39], v[34:35]
	v_cvt_pk_bf16_f32 v34, v36, v37
	v_pk_add_f32 v[32:33], v[32:33], v[42:43]
	v_lshl_add_u64 v[36:37], s[0:1], 0, v[182:183]
	v_pk_add_f32 v[38:39], v[32:33], v[46:47]
	v_cvt_pk_bf16_f32 v32, v48, v49
	v_cvt_pk_bf16_f32 v33, v50, v51
	v_cvt_pk_bf16_f32 v35, v38, v39
	v_lshl_add_u64 v[182:183], v[182:183], 0, s[90:91]
	global_store_dwordx4 v[36:37], v[32:35], off offset:-8
	s_barrier
	s_cbranch_scc0 .LBB0_203
	v_cvt_pk_bf16_f32 v16, v16, v17
	v_cvt_pk_bf16_f32 v17, v18, v19
	v_cvt_pk_bf16_f32 v18, v20, v21
	v_cvt_pk_bf16_f32 v19, v22, v23
	v_cvt_pk_bf16_f32 v0, v0, v1
	v_cvt_pk_bf16_f32 v1, v2, v3
	s_waitcnt vmcnt(22)
	v_mfma_f32_32x32x16_bf16 v[48:63], v[96:99], v[16:19], 0
	v_cvt_pk_bf16_f32 v2, v4, v5
	v_cvt_pk_bf16_f32 v3, v6, v7
	v_cvt_pk_bf16_f32 v4, v8, v9
	v_cvt_pk_bf16_f32 v5, v10, v11
	v_cvt_pk_bf16_f32 v6, v12, v13
	v_cvt_pk_bf16_f32 v7, v14, v15
	s_lshl_b32 s66, s66, 1
	s_waitcnt vmcnt(18)
	v_mfma_f32_32x32x16_bf16 v[32:47], v[100:103], v[16:19], 0
	v_cvt_pk_bf16_f32 v16, v24, v25
	v_cvt_pk_bf16_f32 v17, v26, v27
	v_cvt_pk_bf16_f32 v18, v28, v29
	v_cvt_pk_bf16_f32 v19, v30, v31
	s_add_i32 s23, s23, s64
	s_add_i32 s22, s22, s64
	v_mfma_f32_32x32x16_bf16 v[48:63], v[88:91], v[16:19], v[48:63]
	s_waitcnt vmcnt(17)
	v_mfma_f32_32x32x16_bf16 v[32:47], v[92:95], v[16:19], v[32:47]
	v_mfma_f32_32x32x16_bf16 v[48:63], v[80:83], v[0:3], v[48:63]
	s_waitcnt vmcnt(16)
	v_mfma_f32_32x32x16_bf16 v[32:47], v[84:87], v[0:3], v[32:47]
	s_waitcnt vmcnt(9)
	v_cndmask_b32_e64 v0, v119, v115, s[14:15]
	v_cndmask_b32_e64 v1, v118, v114, s[14:15]
	v_cndmask_b32_e64 v2, v117, v113, s[14:15]
	v_cndmask_b32_e64 v3, v116, v112, s[14:15]
	v_cndmask_b32_e64 v8, v3, v104, s[12:13]
	v_cndmask_b32_e64 v9, v2, v105, s[12:13]
	v_cndmask_b32_e64 v1, v1, v106, s[12:13]
	v_mfma_f32_32x32x16_bf16 v[48:63], v[72:75], v[4:7], v[48:63]
	v_cndmask_b32_e64 v0, v0, v107, s[12:13]
	v_cndmask_b32_e64 v3, v0, v111, s[10:11]
	v_cndmask_b32_e64 v2, v1, v110, s[10:11]
	v_cndmask_b32_e64 v1, v9, v109, s[10:11]
	v_cndmask_b32_e64 v0, v8, v108, s[10:11]
	v_lshl_add_u64 v[8:9], v[164:165], 0, s[66:67]
	s_lshl_b32 s66, s24, 1
	v_mfma_f32_32x32x16_bf16 v[32:47], v[76:79], v[4:7], v[32:47]
	v_lshl_add_u64 v[8:9], v[8:9], 0, s[66:67]
	v_lshl_add_u64 v[8:9], v[8:9], 0, v[186:187]
	s_cmpk_gt_i32 s23, 0x1ff
	v_mfma_f32_32x32x16_bf16 v[48:63], v[64:67], v[0:3], v[48:63]
	v_lshl_add_u64 v[64:65], v[8:9], 0, s[2:3]
	ds_write_b32 v155, v187 offset:32768
	s_nop 9
	ds_write2_b32 v204, v48, v49 offset1:32
	v_mfma_f32_32x32x16_bf16 v[32:47], v[68:71], v[0:3], v[32:47]
	ds_write2_b32 v204, v50, v51 offset0:64 offset1:96
	ds_write2_b32 v205, v52, v53 offset1:32
	ds_write2_b32 v205, v54, v55 offset0:64 offset1:96
	ds_write2_b32 v206, v56, v57 offset1:32
	ds_write2_b32 v206, v58, v59 offset0:64 offset1:96
	ds_write2_b32 v207, v60, v61 offset1:32
	ds_write2_b32 v207, v62, v63 offset0:64 offset1:96
	s_nop 4
	ds_write2_b32 v208, v32, v33 offset1:32
	ds_write2_b32 v208, v34, v35 offset0:64 offset1:96
	ds_write2_b32 v209, v36, v37 offset1:32
	ds_write2_b32 v209, v38, v39 offset0:64 offset1:96
	ds_write2_b32 v210, v40, v41 offset1:32
	ds_write2_b32 v210, v42, v43 offset0:64 offset1:96
	ds_write2_b32 v211, v44, v45 offset1:32
	ds_write2_b32 v211, v46, v47 offset0:64 offset1:96
	s_waitcnt lgkmcnt(0)
	s_barrier
	ds_read_b128 v[0:3], v203 offset:8192
	ds_read_b128 v[4:7], v203
	ds_read_b128 v[8:11], v203 offset:16
	ds_read_b128 v[12:15], v203 offset:16384
	ds_read_b128 v[16:19], v203 offset:24576
	ds_read_b128 v[20:23], v203 offset:8208
	ds_read_b128 v[24:27], v203 offset:16400
	ds_read_b128 v[28:31], v203 offset:24592
	s_waitcnt lgkmcnt(6)
	v_pk_add_f32 v[0:1], v[4:5], v[0:1]
	v_pk_add_f32 v[2:3], v[6:7], v[2:3]
	s_waitcnt lgkmcnt(2)
	v_pk_add_f32 v[4:5], v[8:9], v[20:21]
	v_pk_add_f32 v[0:1], v[0:1], v[12:13]
	v_pk_add_f32 v[2:3], v[2:3], v[14:15]
	s_waitcnt lgkmcnt(1)
	v_pk_add_f32 v[4:5], v[4:5], v[24:25]
	v_pk_add_f32 v[6:7], v[10:11], v[22:23]
	v_pk_add_f32 v[0:1], v[0:1], v[16:17]
	v_pk_add_f32 v[2:3], v[2:3], v[18:19]
	s_waitcnt lgkmcnt(0)
	v_pk_add_f32 v[4:5], v[4:5], v[28:29]
	v_pk_add_f32 v[6:7], v[6:7], v[26:27]
	v_cvt_pk_bf16_f32 v0, v0, v1
	v_pk_add_f32 v[6:7], v[6:7], v[30:31]
	v_cvt_pk_bf16_f32 v1, v2, v3
	v_cvt_pk_bf16_f32 v2, v4, v5
	v_add_co_u32_e32 v4, vcc, 0x3c0000, v64
	v_cvt_pk_bf16_f32 v3, v6, v7
	s_nop 0
	v_addc_co_u32_e32 v5, vcc, 0, v65, vcc
	global_store_dwordx4 v[4:5], v[0:3], off
	s_barrier
	s_cbranch_scc0 .LBB0_198

.LBB0_210:
	s_bfe_u32 s7, s6, 0x20004
	s_and_b32 s0, s6, 15
	s_lshl_b32 s8, s0, 5
	s_lshl_b32 s9, s7, 9
	s_or_b32 s8, s9, s8
	v_or_b32_e32 v0, s8, v178
	s_ashr_i32 s1, s6, 6
	s_lshl_b32 s17, s7, 22
	s_lshl_b32 s18, s1, 19
	s_or_b32 s17, s17, s18
	s_addk_i32 s17, 0x1000
	s_lshl_b32 s19, s7, 23
	s_lshl_b32 s18, s1, 20
	s_or_b32 s19, s19, s18
	s_lshl_b32 s18, s0, 12
	s_or_b32 s19, s19, s18
	s_mov_b64 s[20:21], 0x10000
	v_lshlrev_b32_e32 v186, 14, v0
	v_lshl_add_u32 v0, s7, 8, v179
	s_lshl_b32 s8, s1, 10
	v_ashrrev_i32_e32 v1, 31, v0
	s_ashr_i32 s9, s8, 31
	v_lshlrev_b64 v[0:1], 14, v[0:1]
	s_lshl_b64 s[8:9], s[8:9], 1
	v_lshl_add_u64 v[0:1], s[10:11], 0, v[0:1]
	v_lshl_add_u64 v[0:1], v[0:1], 0, s[8:9]
	v_mov_b32_e32 v161, v187
	v_lshl_add_u64 v[166:167], v[0:1], 0, v[160:161]
	v_lshrrev_b32_e32 v188, 6, v152
	v_and_b32_e32 v190, 63, v152
	v_lshlrev_b32_e32 v188, 13, v188
	v_lshl_or_b32 v188, v190, 4, v188
	v_add_u32_e32 v220, s17, v188
	v_mov_b32_e32 v221, 0
	v_lshl_add_u64 v[220:221], s[10:11], 0, v[220:221]
	v_add_co_u32_e32 v222, vcc, 0x8000, v220
	s_nop 1
	v_addc_co_u32_e32 v223, vcc, 0, v221, vcc
	v_add_co_u32_e32 v224, vcc, 0x8000, v222
	s_nop 1
	v_addc_co_u32_e32 v225, vcc, 0, v223, vcc
	v_add_co_u32_e32 v226, vcc, 0x8000, v224
	s_nop 1
	v_addc_co_u32_e32 v227, vcc, 0, v225, vcc
	v_add_co_u32_e32 v228, vcc, 0x8000, v226
	s_nop 1
	v_addc_co_u32_e32 v229, vcc, 0, v227, vcc
	v_add_co_u32_e32 v230, vcc, 0x8000, v228
	s_nop 1
	v_addc_co_u32_e32 v231, vcc, 0, v229, vcc
	v_add_co_u32_e32 v232, vcc, 0x8000, v230
	s_nop 1
	v_addc_co_u32_e32 v233, vcc, 0, v231, vcc
	v_add_co_u32_e32 v234, vcc, 0x8000, v232
	s_nop 1
	v_addc_co_u32_e32 v235, vcc, 0, v233, vcc
	v_add_co_u32_e32 v236, vcc, 0x8000, v234
	s_nop 1
	v_addc_co_u32_e32 v237, vcc, 0, v235, vcc
	v_add_co_u32_e32 v238, vcc, 0x8000, v236
	s_nop 1
	v_addc_co_u32_e32 v239, vcc, 0, v237, vcc
	v_add_co_u32_e32 v240, vcc, 0x8000, v238
	s_nop 1
	v_addc_co_u32_e32 v241, vcc, 0, v239, vcc
	v_add_co_u32_e32 v244, vcc, 0x8000, v240
	s_nop 1
	v_addc_co_u32_e32 v245, vcc, 0, v241, vcc
	v_add_co_u32_e32 v246, vcc, 0x8000, v244
	s_nop 1
	v_addc_co_u32_e32 v247, vcc, 0, v245, vcc
	v_add_co_u32_e32 v248, vcc, 0x8000, v246
	s_nop 1
	v_addc_co_u32_e32 v249, vcc, 0, v247, vcc
	v_add_co_u32_e32 v250, vcc, 0x8000, v248
	s_nop 1
	v_addc_co_u32_e32 v251, vcc, 0, v249, vcc
	v_add_co_u32_e32 v252, vcc, 0x8000, v250
	s_nop 1
	v_addc_co_u32_e32 v253, vcc, 0, v251, vcc
	global_load_dwordx4 v[0:3], v[220:221], off offset:-4096
	v_lshl_add_u64 v[4:5], s[2:3], 0, v[186:187]
	v_lshl_add_u64 v[4:5], v[4:5], 0, s[8:9]
	v_lshlrev_b32_e32 v188, 4, v190
	v_add_u32_e32 v168, s19, v188
	v_mov_b32_e32 v169, 0
	v_lshl_add_u64 v[168:169], s[2:3], 0, v[168:169]
	global_load_dwordx4 v[4:7], v[168:169], off
	v_add_co_u32_e32 v164, vcc, s79, v166
	s_lshl_b32 s8, s1, 4
	s_nop 0
	v_addc_co_u32_e32 v165, vcc, 0, v167, vcc
	global_load_dwordx4 v[8:11], v[220:221], off
	global_load_dwordx4 v[32:35], v[220:221], off offset:-3072
	global_load_dwordx4 v[36:39], v[168:169], off offset:1024
	global_load_dwordx4 v[40:43], v[220:221], off offset:1024
	global_load_dwordx4 v[44:47], v[220:221], off offset:-2048
	global_load_dwordx4 v[52:55], v[168:169], off offset:2048
	global_load_dwordx4 v[56:59], v[220:221], off offset:2048
	global_load_dwordx4 v[60:63], v[220:221], off offset:-1024
	global_load_dwordx4 v[64:67], v[168:169], off offset:3072
	v_lshl_add_u64 v[168:169], v[168:169], 0, s[20:21]
	s_ashr_i32 s9, s8, 31
	s_lshl_b64 s[8:9], s[8:9], 12
	s_add_u32 s14, s4, s8
	s_addc_u32 s15, s5, s9
	s_lshl_b32 s16, s7, 10
	global_load_dwordx4 v[68:71], v[220:221], off offset:3072
	s_add_u32 s14, s14, s16
	s_addc_u32 s15, s15, 0
	v_mov_b32_e32 v163, v187
	v_lshl_add_u64 v[12:13], v[154:155], 2, s[14:15]
	v_lshl_add_u64 v[170:171], v[12:13], 0, v[162:163]
	global_load_dwordx4 v[72:75], v[170:171], off offset:96
	global_load_dwordx4 v[76:79], v[170:171], off offset:64
	global_load_dwordx4 v[80:83], v[222:223], off offset:-4096
	global_load_dwordx4 v[84:87], v[170:171], off offset:32
	global_load_dwordx4 v[88:91], v[170:171], off
	global_load_dwordx4 v[92:95], v[168:169], off
	global_load_dwordx4 v[96:99], v[170:171], off offset:224
	global_load_dwordx4 v[180:183], v[170:171], off offset:192
	global_load_dwordx4 v[192:195], v[222:223], off
	global_load_dwordx4 v[196:199], v[170:171], off offset:160
	global_load_dwordx4 v[200:203], v[170:171], off offset:128
	global_load_dwordx4 v[204:207], v[222:223], off offset:-3072
	global_load_dwordx4 v[208:211], v[168:169], off offset:1024
	s_movk_i32 s14, 0x3000
	s_lshl_b32 s1, s1, 2
	s_or_b32 s7, s1, s7
	s_lshl_b32 s1, s7, 4
	s_waitcnt vmcnt(23) lgkmcnt(0)
	v_mfma_f32_32x32x16_bf16 v[16:31], v[0:3], v[4:7], 0
	s_waitcnt vmcnt(22)
	v_mfma_f32_32x32x16_bf16 v[0:15], v[8:11], v[4:7], 0
	s_waitcnt vmcnt(20)
	v_mfma_f32_32x32x16_bf16 v[16:31], v[32:35], v[36:39], v[16:31]
	global_load_dwordx4 v[32:35], v[222:223], off offset:1024
	s_waitcnt vmcnt(20)
	v_mfma_f32_32x32x16_bf16 v[0:15], v[40:43], v[36:39], v[0:15]
	global_load_dwordx4 v[40:43], v[222:223], off offset:-2048
	global_load_dwordx4 v[212:215], v[168:169], off offset:2048
	global_load_dwordx4 v[216:219], v[222:223], off offset:2048
	global_load_dwordx4 v[48:51], v[222:223], off offset:-1024
	global_load_dwordx4 v[108:111], v[224:225], off offset:-4096
	global_load_dwordx4 v[116:119], v[168:169], off offset:3072
	v_lshl_add_u64 v[168:169], v[168:169], 0, s[20:21]
	global_load_dwordx4 v[124:127], v[222:223], off offset:3072
	global_load_dwordx4 v[100:103], v[224:225], off
	global_load_dwordx4 v[104:107], v[168:169], off
	v_add_co_u32_e32 v36, vcc, s29, v170
	s_nop 1
	v_addc_co_u32_e32 v37, vcc, 0, v171, vcc
	s_waitcnt vmcnt(27)
	v_mfma_f32_32x32x16_bf16 v[16:31], v[44:47], v[52:55], v[16:31]
	v_add_co_u32_e32 v174, vcc, s76, v170
	s_nop 1
	v_addc_co_u32_e32 v175, vcc, 0, v171, vcc
	global_load_dwordx4 v[128:131], v[174:175], off offset:-4096
	global_load_dwordx4 v[136:139], v[36:37], off offset:32
	global_load_dwordx4 v[144:147], v[36:37], off offset:64
	global_load_dwordx4 v[148:151], v[36:37], off offset:96
	global_load_dwordx4 v[112:115], v[36:37], off offset:128
	global_load_dwordx4 v[120:123], v[36:37], off offset:160
	global_load_dwordx4 v[132:135], v[36:37], off offset:192
	global_load_dwordx4 v[140:143], v[36:37], off offset:224
	s_waitcnt vmcnt(32)
	v_mfma_f32_32x32x16_bf16 v[16:31], v[60:63], v[64:67], v[16:31]
	v_add_co_u32_e32 v176, vcc, s14, v170
	s_mov_b32 s14, 0xf000
	s_nop 0
	v_addc_co_u32_e32 v177, vcc, 0, v171, vcc
	v_add_co_u32_e32 v172, vcc, s14, v170
	v_mfma_f32_32x32x16_bf16 v[0:15], v[56:59], v[52:55], v[0:15]
	s_waitcnt vmcnt(30)
	s_nop 4
	v_mul_f32_e64 v30, v74, v30
	v_mul_f32_e64 v31, v75, v31
	v_mul_f32_e64 v28, v72, v28
	v_mul_f32_e64 v29, v73, v29
	global_load_dwordx4 v[36:39], v[224:225], off offset:-3072
	global_load_dwordx4 v[72:75], v[168:169], off offset:1024
	s_waitcnt vmcnt(31)
	v_pk_mul_f32 v[26:27], v[78:79], v[26:27]
	v_pk_mul_f32 v[24:25], v[76:77], v[24:25]
	global_load_dwordx4 v[76:79], v[224:225], off offset:1024
	s_waitcnt vmcnt(30)
	v_pk_mul_f32 v[22:23], v[86:87], v[22:23]
	v_mfma_f32_32x32x16_bf16 v[0:15], v[68:71], v[64:67], v[0:15]
	global_load_dwordx4 v[68:71], v[224:225], off offset:-2048
	global_load_dwordx4 v[52:55], v[168:169], off offset:2048
	global_load_dwordx4 v[64:67], v[224:225], off offset:-1024
	global_load_dwordx4 v[44:47], v[168:169], off offset:3072
	v_lshl_add_u64 v[168:169], v[168:169], 0, s[20:21]
	global_load_dwordx4 v[60:63], v[224:225], off offset:2048
	v_pk_mul_f32 v[20:21], v[84:85], v[20:21]
	s_waitcnt vmcnt(34)
	v_pk_mul_f32 v[18:19], v[90:91], v[18:19]
	v_pk_mul_f32 v[16:17], v[88:89], v[16:17]
	v_addc_co_u32_e32 v173, vcc, 0, v171, vcc
	s_waitcnt vmcnt(33)
	v_mfma_f32_32x32x16_bf16 v[16:31], v[80:83], v[92:95], v[16:31]
	s_waitcnt vmcnt(32)
	v_mul_f32_e64 v14, v98, v14
	v_mul_f32_e64 v15, v99, v15
	v_mul_f32_e64 v12, v96, v12
	v_mul_f32_e64 v13, v97, v13
	s_waitcnt vmcnt(31)
	v_pk_mul_f32 v[10:11], v[182:183], v[10:11]
	v_pk_mul_f32 v[8:9], v[180:181], v[8:9]
	s_waitcnt vmcnt(29)
	v_pk_mul_f32 v[6:7], v[198:199], v[6:7]
	v_pk_mul_f32 v[4:5], v[196:197], v[4:5]
	s_waitcnt vmcnt(28)
	v_pk_mul_f32 v[2:3], v[202:203], v[2:3]
	v_pk_mul_f32 v[0:1], v[200:201], v[0:1]
	s_waitcnt vmcnt(26)
	v_mfma_f32_32x32x16_bf16 v[16:31], v[204:207], v[208:211], v[16:31]
	s_movk_i32 s14, 0x4000
	v_mfma_f32_32x32x16_bf16 v[0:15], v[192:195], v[92:95], v[0:15]
	s_waitcnt vmcnt(25)
	v_mfma_f32_32x32x16_bf16 v[0:15], v[32:35], v[208:211], v[0:15]
	s_waitcnt vmcnt(23)
	v_mfma_f32_32x32x16_bf16 v[16:31], v[40:43], v[212:215], v[16:31]
	global_load_dwordx4 v[56:59], v[224:225], off offset:3072
	global_load_dwordx4 v[40:43], v[226:227], off offset:-4096
	global_load_dwordx4 v[32:35], v[168:169], off
	s_waitcnt vmcnt(25)
	v_mfma_f32_32x32x16_bf16 v[0:15], v[216:219], v[212:215], v[0:15]
	s_waitcnt vmcnt(22)
	v_mfma_f32_32x32x16_bf16 v[16:31], v[48:51], v[116:119], v[16:31]
	global_load_dwordx4 v[92:95], v[174:175], off offset:64
	global_load_dwordx4 v[96:99], v[174:175], off offset:96
	global_load_dwordx4 v[84:87], v[174:175], off
	global_load_dwordx4 v[88:91], v[174:175], off offset:32
	global_load_dwordx4 v[80:83], v[176:177], off offset:32
	global_load_dwordx4 v[48:51], v[172:173], off offset:224
	s_waitcnt vmcnt(21)
	s_nop 4
	v_pk_mul_f32 v[30:31], v[150:151], v[30:31]
	v_mfma_f32_32x32x16_bf16 v[0:15], v[124:127], v[116:119], v[0:15]
	v_mul_f32_e64 v28, v148, v28
	v_mul_f32_e64 v29, v149, v29
	v_mul_f32_e64 v26, v146, v26
	v_mul_f32_e64 v27, v147, v27
	v_mul_f32_e64 v24, v144, v24
	v_mul_f32_e64 v25, v145, v25
	v_pk_mul_f32 v[22:23], v[138:139], v[22:23]
	v_pk_mul_f32 v[20:21], v[136:137], v[20:21]
	v_pk_mul_f32 v[18:19], v[130:131], v[18:19]
	v_pk_mul_f32 v[16:17], v[128:129], v[16:17]
	s_waitcnt vmcnt(17)
	s_nop 0
	v_pk_mul_f32 v[14:15], v[142:143], v[14:15]
	v_pk_mul_f32 v[12:13], v[140:141], v[12:13]
	v_mfma_f32_32x32x16_bf16 v[16:31], v[108:111], v[104:107], v[16:31]
	v_mul_f32_e64 v10, v134, v10
	v_mul_f32_e64 v11, v135, v11
	v_mul_f32_e64 v8, v132, v8
	v_mul_f32_e64 v9, v133, v9
	v_mul_f32_e64 v6, v122, v6
	v_mul_f32_e64 v7, v123, v7
	v_pk_mul_f32 v[4:5], v[120:121], v[4:5]
	v_pk_mul_f32 v[2:3], v[114:115], v[2:3]
	v_pk_mul_f32 v[0:1], v[112:113], v[0:1]
	v_add_co_u32_e32 v140, vcc, s14, v170
	s_nop 0
	v_mfma_f32_32x32x16_bf16 v[0:15], v[100:103], v[104:107], v[0:15]
	global_load_dwordx4 v[100:103], v[226:227], off offset:-3072
	global_load_dwordx4 v[104:107], v[168:169], off offset:1024
	v_addc_co_u32_e32 v141, vcc, 0, v171, vcc
	s_movk_i32 s14, 0x5000
	s_waitcnt vmcnt(17)
	v_mfma_f32_32x32x16_bf16 v[16:31], v[36:39], v[72:75], v[16:31]
	global_load_dwordx4 v[36:39], v[226:227], off offset:-2048
	global_load_dwordx4 v[108:111], v[168:169], off offset:2048
	s_waitcnt vmcnt(16)
	v_mfma_f32_32x32x16_bf16 v[16:31], v[68:71], v[52:55], v[16:31]
	v_mfma_f32_32x32x16_bf16 v[0:15], v[76:79], v[72:75], v[0:15]
	global_load_dwordx4 v[72:75], v[226:227], off offset:-1024
	global_load_dwordx4 v[76:79], v[168:169], off offset:3072
	v_lshl_add_u64 v[168:169], v[168:169], 0, s[20:21]
	global_load_dwordx4 v[112:115], v[174:175], off offset:224
	global_load_dwordx4 v[116:119], v[174:175], off offset:192
	global_load_dwordx4 v[120:123], v[174:175], off offset:160
	global_load_dwordx4 v[68:71], v[226:227], off
	global_load_dwordx4 v[124:127], v[174:175], off offset:128
	s_waitcnt vmcnt(21)
	v_mfma_f32_32x32x16_bf16 v[16:31], v[64:67], v[44:47], v[16:31]
	global_load_dwordx4 v[64:67], v[226:227], off offset:1024
	s_waitcnt vmcnt(21)
	v_mfma_f32_32x32x16_bf16 v[0:15], v[60:63], v[52:55], v[0:15]
	global_load_dwordx4 v[52:55], v[226:227], off offset:2048
	global_load_dwordx4 v[60:63], v[226:227], off offset:3072
	s_waitcnt vmcnt(19)
	s_nop 5
	v_mul_f32_e64 v26, v94, v26
	v_mul_f32_e64 v27, v95, v27
	v_mfma_f32_32x32x16_bf16 v[0:15], v[56:59], v[44:47], v[0:15]
	global_load_dwordx4 v[44:47], v[228:229], off offset:-4096
	s_waitcnt vmcnt(19)
	v_mul_f32_e64 v30, v98, v30
	v_mul_f32_e64 v31, v99, v31
	v_mul_f32_e64 v28, v96, v28
	v_mul_f32_e64 v29, v97, v29
	v_pk_mul_f32 v[24:25], v[92:93], v[24:25]
	global_load_dwordx4 v[56:59], v[176:177], off offset:64
	global_load_dwordx4 v[92:95], v[176:177], off offset:96
	s_waitcnt vmcnt(19)
	v_pk_mul_f32 v[22:23], v[90:91], v[22:23]
	v_pk_mul_f32 v[20:21], v[88:89], v[20:21]
	global_load_dwordx4 v[88:91], v[140:141], off offset:-4096
	v_pk_mul_f32 v[18:19], v[86:87], v[18:19]
	v_pk_mul_f32 v[16:17], v[84:85], v[16:17]
	s_waitcnt vmcnt(11)
	v_pk_mul_f32 v[14:15], v[114:115], v[14:15]
	v_mfma_f32_32x32x16_bf16 v[16:31], v[40:43], v[32:35], v[16:31]
	global_load_dwordx4 v[40:43], v[168:169], off
	global_load_dwordx4 v[84:87], v[228:229], off offset:-3072
	global_load_dwordx4 v[96:99], v[168:169], off offset:1024
	v_mul_f32_e64 v12, v112, v12
	v_mul_f32_e64 v13, v113, v13
	s_waitcnt vmcnt(13)
	v_pk_mul_f32 v[10:11], v[118:119], v[10:11]
	v_pk_mul_f32 v[8:9], v[116:117], v[8:9]
	s_waitcnt vmcnt(12)
	v_pk_mul_f32 v[6:7], v[122:123], v[6:7]
	v_pk_mul_f32 v[4:5], v[120:121], v[4:5]
	v_mfma_f32_32x32x16_bf16 v[16:31], v[100:103], v[104:107], v[16:31]
	s_waitcnt vmcnt(10)
	v_mul_f32_e64 v2, v126, v2
	v_mul_f32_e64 v3, v127, v3
	v_mul_f32_e64 v0, v124, v0
	v_mul_f32_e64 v1, v125, v1
	v_mfma_f32_32x32x16_bf16 v[16:31], v[36:39], v[108:111], v[16:31]
	global_load_dwordx4 v[36:39], v[228:229], off offset:-2048
	global_load_dwordx4 v[100:103], v[168:169], off offset:2048
	global_load_dwordx4 v[128:131], v[228:229], off offset:-1024
	global_load_dwordx4 v[132:135], v[168:169], off offset:3072
	v_lshl_add_u64 v[168:169], v[168:169], 0, s[20:21]
	global_load_dwordx4 v[136:139], v[228:229], off
	v_mfma_f32_32x32x16_bf16 v[0:15], v[68:71], v[32:35], v[0:15]
	v_mfma_f32_32x32x16_bf16 v[16:31], v[72:75], v[76:79], v[16:31]
	global_load_dwordx4 v[72:75], v[176:177], off offset:192
	global_load_dwordx4 v[112:115], v[176:177], off offset:224
	global_load_dwordx4 v[32:35], v[176:177], off offset:160
	global_load_dwordx4 v[68:71], v[176:177], off offset:128
	s_waitcnt vmcnt(18)
	v_mfma_f32_32x32x16_bf16 v[0:15], v[64:67], v[104:107], v[0:15]
	global_load_dwordx4 v[64:67], v[228:229], off offset:1024
	s_waitcnt vmcnt(14)
	s_nop 3
	v_mul_f32_e64 v30, v94, v30
	v_mul_f32_e64 v31, v95, v31
	v_mul_f32_e64 v28, v92, v28
	v_mul_f32_e64 v29, v93, v29
	v_pk_mul_f32 v[26:27], v[58:59], v[26:27]
	v_pk_mul_f32 v[24:25], v[56:57], v[24:25]
	v_pk_mul_f32 v[22:23], v[82:83], v[22:23]
	v_pk_mul_f32 v[20:21], v[80:81], v[20:21]
	v_mfma_f32_32x32x16_bf16 v[0:15], v[52:55], v[108:111], v[0:15]
	global_load_dwordx4 v[52:55], v[228:229], off offset:2048
	global_load_dwordx4 v[104:107], v[228:229], off offset:3072
	s_waitcnt vmcnt(15)
	v_mul_f32_e64 v18, v90, v18
	v_mul_f32_e64 v19, v91, v19
	v_pk_mul_f32 v[16:17], v[88:89], v[16:17]
	global_load_dwordx4 v[56:59], v[140:141], off
	s_waitcnt vmcnt(15)
	v_mfma_f32_32x32x16_bf16 v[16:31], v[44:47], v[40:43], v[16:31]
	v_mfma_f32_32x32x16_bf16 v[0:15], v[60:63], v[76:79], v[0:15]
	global_load_dwordx4 v[60:63], v[140:141], off offset:96
	global_load_dwordx4 v[76:79], v[140:141], off offset:64
	global_load_dwordx4 v[44:47], v[140:141], off offset:32
	global_load_dwordx4 v[80:83], v[230:231], off offset:-4096
	s_waitcnt vmcnt(17)
	v_mfma_f32_32x32x16_bf16 v[16:31], v[84:87], v[96:99], v[16:31]
	global_load_dwordx4 v[84:87], v[168:169], off
	global_load_dwordx4 v[88:91], v[230:231], off offset:-3072
	s_waitcnt vmcnt(13)
	s_nop 2
	v_mul_f32_e64 v10, v74, v10
	v_mul_f32_e64 v11, v75, v11
	v_mfma_f32_32x32x16_bf16 v[16:31], v[36:39], v[100:103], v[16:31]
	global_load_dwordx4 v[36:39], v[168:169], off offset:1024
	global_load_dwordx4 v[92:95], v[230:231], off offset:-2048
	global_load_dwordx4 v[108:111], v[168:169], off offset:2048
	global_load_dwordx4 v[116:119], v[230:231], off offset:-1024
	s_waitcnt vmcnt(16)
	v_pk_mul_f32 v[14:15], v[114:115], v[14:15]
	v_pk_mul_f32 v[12:13], v[112:113], v[12:13]
	v_pk_mul_f32 v[8:9], v[72:73], v[8:9]
	s_waitcnt vmcnt(15)
	v_pk_mul_f32 v[6:7], v[34:35], v[6:7]
	v_pk_mul_f32 v[4:5], v[32:33], v[4:5]
	s_waitcnt vmcnt(14)
	v_pk_mul_f32 v[2:3], v[70:71], v[2:3]
	v_pk_mul_f32 v[0:1], v[68:69], v[0:1]
	v_mfma_f32_32x32x16_bf16 v[16:31], v[128:131], v[132:135], v[16:31]
	s_nop 0
	v_mfma_f32_32x32x16_bf16 v[0:15], v[136:139], v[40:43], v[0:15]
	global_load_dwordx4 v[32:35], v[168:169], off offset:3072
	v_lshl_add_u64 v[168:169], v[168:169], 0, s[20:21]
	global_load_dwordx4 v[40:43], v[140:141], off offset:224
	global_load_dwordx4 v[68:71], v[140:141], off offset:192
	global_load_dwordx4 v[72:75], v[140:141], off offset:160
	s_waitcnt vmcnt(14)
	s_nop 4
	v_pk_mul_f32 v[18:19], v[58:59], v[18:19]
	v_pk_mul_f32 v[16:17], v[56:57], v[16:17]
	s_waitcnt vmcnt(13)
	v_pk_mul_f32 v[30:31], v[62:63], v[30:31]
	v_mfma_f32_32x32x16_bf16 v[0:15], v[64:67], v[96:99], v[0:15]
	global_load_dwordx4 v[64:67], v[230:231], off
	global_load_dwordx4 v[96:99], v[140:141], off offset:128
	v_add_co_u32_e32 v140, vcc, s14, v170
	s_movk_i32 s14, 0x6000
	s_nop 0
	v_addc_co_u32_e32 v141, vcc, 0, v171, vcc
	v_add_co_u32_e32 v142, vcc, s14, v170
	v_mfma_f32_32x32x16_bf16 v[0:15], v[52:55], v[100:103], v[0:15]
	global_load_dwordx4 v[52:55], v[230:231], off offset:1024
	global_load_dwordx4 v[100:103], v[230:231], off offset:2048
	global_load_dwordx4 v[112:115], v[230:231], off offset:3072
	v_addc_co_u32_e32 v143, vcc, 0, v171, vcc
	v_mul_f32_e64 v28, v60, v28
	v_mul_f32_e64 v29, v61, v29
	s_waitcnt vmcnt(17)
	v_pk_mul_f32 v[26:27], v[78:79], v[26:27]
	v_pk_mul_f32 v[24:25], v[76:77], v[24:25]
	s_waitcnt vmcnt(16)
	v_pk_mul_f32 v[22:23], v[46:47], v[22:23]
	v_mfma_f32_32x32x16_bf16 v[0:15], v[104:107], v[132:135], v[0:15]
	global_load_dwordx4 v[104:107], v[232:233], off offset:-4096
	v_mul_f32_e64 v20, v44, v20
	v_mul_f32_e64 v21, v45, v21
	global_load_dwordx4 v[44:47], v[140:141], off offset:96
	global_load_dwordx4 v[56:59], v[140:141], off offset:32
	global_load_dwordx4 v[60:63], v[140:141], off offset:64
	global_load_dwordx4 v[76:79], v[142:143], off offset:-4096
	s_movk_i32 s14, 0x7000
	v_add_co_u32_e32 v174, vcc, s14, v170
	s_waitcnt vmcnt(19)
	v_mfma_f32_32x32x16_bf16 v[16:31], v[80:83], v[84:87], v[16:31]
	global_load_dwordx4 v[80:83], v[168:169], off
	global_load_dwordx4 v[120:123], v[232:233], off offset:-3072
	v_addc_co_u32_e32 v175, vcc, 0, v171, vcc
	s_mov_b32 s14, 0x8000
	v_add_co_u32_e32 v176, vcc, s14, v170
	s_mov_b32 s14, 0x9000
	s_waitcnt vmcnt(19)
	v_mfma_f32_32x32x16_bf16 v[16:31], v[88:91], v[36:39], v[16:31]
	global_load_dwordx4 v[88:91], v[168:169], off offset:1024
	global_load_dwordx4 v[124:127], v[232:233], off offset:-2048
	v_addc_co_u32_e32 v177, vcc, 0, v171, vcc
	s_waitcnt vmcnt(16)
	v_mul_f32_e64 v14, v42, v14
	v_mul_f32_e64 v15, v43, v15
	v_pk_mul_f32 v[12:13], v[40:41], v[12:13]
	s_waitcnt vmcnt(15)
	v_pk_mul_f32 v[10:11], v[70:71], v[10:11]
	v_mfma_f32_32x32x16_bf16 v[16:31], v[92:95], v[108:111], v[16:31]
	v_mul_f32_e64 v8, v68, v8
	v_mul_f32_e64 v9, v69, v9
	s_waitcnt vmcnt(14)
	v_mul_f32_e64 v6, v74, v6
	v_mul_f32_e64 v7, v75, v7
	v_pk_mul_f32 v[4:5], v[72:73], v[4:5]
	global_load_dwordx4 v[92:95], v[168:169], off offset:2048
	global_load_dwordx4 v[128:131], v[232:233], off offset:-1024
	global_load_dwordx4 v[132:135], v[168:169], off offset:3072
	v_lshl_add_u64 v[168:169], v[168:169], 0, s[20:21]
	global_load_dwordx4 v[136:139], v[232:233], off
	s_waitcnt vmcnt(16)
	v_pk_mul_f32 v[2:3], v[98:99], v[2:3]
	v_pk_mul_f32 v[0:1], v[96:97], v[0:1]
	v_mfma_f32_32x32x16_bf16 v[16:31], v[116:119], v[32:35], v[16:31]
	global_load_dwordx4 v[40:43], v[140:141], off offset:224
	global_load_dwordx4 v[68:71], v[140:141], off offset:160
	global_load_dwordx4 v[116:119], v[140:141], off offset:192
	v_mfma_f32_32x32x16_bf16 v[0:15], v[64:67], v[84:87], v[0:15]
	global_load_dwordx4 v[64:67], v[140:141], off offset:128
	s_waitcnt vmcnt(15)
	s_nop 5
	v_mul_f32_e64 v30, v46, v30
	v_mul_f32_e64 v31, v47, v31
	v_mfma_f32_32x32x16_bf16 v[0:15], v[52:55], v[36:39], v[0:15]
	global_load_dwordx4 v[36:39], v[232:233], off offset:1024
	global_load_dwordx4 v[52:55], v[232:233], off offset:2048
	global_load_dwordx4 v[72:75], v[232:233], off offset:3072
	v_mul_f32_e64 v28, v44, v28
	v_mul_f32_e64 v29, v45, v29
	s_waitcnt vmcnt(16)
	v_pk_mul_f32 v[26:27], v[62:63], v[26:27]
	v_pk_mul_f32 v[24:25], v[60:61], v[24:25]
	v_pk_mul_f32 v[22:23], v[58:59], v[22:23]
	v_pk_mul_f32 v[20:21], v[56:57], v[20:21]
	v_mfma_f32_32x32x16_bf16 v[0:15], v[100:103], v[108:111], v[0:15]
	s_waitcnt vmcnt(15)
	v_mul_f32_e64 v18, v78, v18
	v_mul_f32_e64 v19, v79, v19
	v_mul_f32_e64 v16, v76, v16
	v_mul_f32_e64 v17, v77, v17
	v_mfma_f32_32x32x16_bf16 v[0:15], v[112:115], v[32:35], v[0:15]
	global_load_dwordx4 v[32:35], v[142:143], off offset:96
	global_load_dwordx4 v[44:47], v[142:143], off offset:64
	global_load_dwordx4 v[56:59], v[234:235], off offset:-4096
	global_load_dwordx4 v[60:63], v[142:143], off offset:32
	global_load_dwordx4 v[76:79], v[142:143], off
	global_load_dwordx4 v[84:87], v[168:169], off
	global_load_dwordx4 v[96:99], v[234:235], off offset:-3072
	s_waitcnt vmcnt(13)
	s_nop 3
	v_pk_mul_f32 v[14:15], v[42:43], v[14:15]
	v_mfma_f32_32x32x16_bf16 v[16:31], v[104:107], v[80:83], v[16:31]
	v_mul_f32_e64 v12, v40, v12
	v_mul_f32_e64 v13, v41, v13
	s_waitcnt vmcnt(11)
	v_mul_f32_e64 v10, v118, v10
	v_mul_f32_e64 v11, v119, v11
	v_pk_mul_f32 v[8:9], v[116:117], v[8:9]
	v_pk_mul_f32 v[6:7], v[70:71], v[6:7]
	v_pk_mul_f32 v[4:5], v[68:69], v[4:5]
	s_waitcnt vmcnt(10)
	v_pk_mul_f32 v[2:3], v[66:67], v[2:3]
	v_mfma_f32_32x32x16_bf16 v[16:31], v[120:123], v[88:91], v[16:31]
	global_load_dwordx4 v[100:103], v[168:169], off offset:1024
	global_load_dwordx4 v[104:107], v[234:235], off offset:-2048
	global_load_dwordx4 v[108:111], v[168:169], off offset:2048
	global_load_dwordx4 v[112:115], v[168:169], off offset:3072
	v_lshl_add_u64 v[168:169], v[168:169], 0, s[20:21]
	global_load_dwordx4 v[120:123], v[234:235], off offset:-1024
	v_pk_mul_f32 v[0:1], v[64:65], v[0:1]
	s_nop 1
	v_mfma_f32_32x32x16_bf16 v[0:15], v[136:139], v[80:83], v[0:15]
	v_mfma_f32_32x32x16_bf16 v[16:31], v[124:127], v[92:95], v[16:31]
	global_load_dwordx4 v[124:127], v[174:175], off offset:32
	global_load_dwordx4 v[40:43], v[142:143], off offset:192
	global_load_dwordx4 v[116:119], v[142:143], off offset:224
	global_load_dwordx4 v[64:67], v[142:143], off offset:160
	global_load_dwordx4 v[68:71], v[234:235], off
	global_load_dwordx4 v[80:83], v[142:143], off offset:128
	s_waitcnt vmcnt(20)
	v_mfma_f32_32x32x16_bf16 v[0:15], v[36:39], v[88:91], v[0:15]
	global_load_dwordx4 v[88:91], v[234:235], off offset:1024
	s_waitcnt vmcnt(20)
	v_mfma_f32_32x32x16_bf16 v[0:15], v[52:55], v[92:95], v[0:15]
	global_load_dwordx4 v[52:55], v[234:235], off offset:2048
	global_load_dwordx4 v[92:95], v[234:235], off offset:3072
	v_mfma_f32_32x32x16_bf16 v[16:31], v[128:131], v[132:135], v[16:31]
	s_waitcnt vmcnt(21)
	v_mfma_f32_32x32x16_bf16 v[0:15], v[72:75], v[132:135], v[0:15]
	s_waitcnt vmcnt(20)
	s_nop 8
	v_mul_f32_e64 v30, v34, v30
	v_mul_f32_e64 v31, v35, v31
	v_mul_f32_e64 v28, v32, v28
	v_mul_f32_e64 v29, v33, v29
	s_waitcnt vmcnt(19)
	v_pk_mul_f32 v[26:27], v[46:47], v[26:27]
	v_pk_mul_f32 v[24:25], v[44:45], v[24:25]
	s_waitcnt vmcnt(17)
	v_pk_mul_f32 v[22:23], v[62:63], v[22:23]
	v_pk_mul_f32 v[20:21], v[60:61], v[20:21]
	s_waitcnt vmcnt(16)
	v_pk_mul_f32 v[18:19], v[78:79], v[18:19]
	v_pk_mul_f32 v[16:17], v[76:77], v[16:17]
	s_waitcnt vmcnt(7)
	v_pk_mul_f32 v[42:43], v[42:43], v[10:11]
	v_mfma_f32_32x32x16_bf16 v[16:31], v[56:59], v[84:87], v[16:31]
	global_load_dwordx4 v[56:59], v[174:175], off offset:96
	global_load_dwordx4 v[60:63], v[174:175], off offset:64
	global_load_dwordx4 v[72:75], v[236:237], off offset:-4096
	global_load_dwordx4 v[76:79], v[176:177], off offset:-4096
	s_waitcnt vmcnt(10)
	v_pk_mul_f32 v[46:47], v[118:119], v[14:15]
	v_pk_mul_f32 v[44:45], v[116:117], v[12:13]
	v_pk_mul_f32 v[40:41], v[40:41], v[8:9]
	s_waitcnt vmcnt(9)
	v_pk_mul_f32 v[38:39], v[66:67], v[6:7]
	v_pk_mul_f32 v[36:37], v[64:65], v[4:5]
	v_mfma_f32_32x32x16_bf16 v[16:31], v[96:99], v[100:103], v[16:31]
	global_load_dwordx4 v[96:99], v[168:169], off
	global_load_dwordx4 v[128:131], v[236:237], off offset:-3072
	s_waitcnt vmcnt(9)
	v_mul_f32_e64 v34, v82, v2
	v_mul_f32_e64 v35, v83, v3
	v_pk_mul_f32 v[32:33], v[80:81], v[0:1]
	s_nop 1
	v_mfma_f32_32x32x16_bf16 v[32:47], v[68:71], v[84:87], v[32:47]
	v_mfma_f32_32x32x16_bf16 v[16:31], v[104:107], v[108:111], v[16:31]
	global_load_dwordx4 v[104:107], v[168:169], off offset:1024
	global_load_dwordx4 v[132:135], v[236:237], off offset:-2048
	global_load_dwordx4 v[136:139], v[236:237], off offset:-1024
	global_load_dwordx4 v[140:143], v[236:237], off
	global_load_dwordx4 v[144:147], v[168:169], off offset:3072
	global_load_dwordx4 v[148:151], v[168:169], off offset:2048
	v_lshl_add_u64 v[168:169], v[168:169], 0, s[20:21]
	global_load_dwordx4 v[64:67], v[174:175], off offset:192
	global_load_dwordx4 v[116:119], v[174:175], off offset:224
	global_load_dwordx4 v[68:71], v[174:175], off offset:160
	global_load_dwordx4 v[80:83], v[174:175], off offset:128
	global_load_dwordx4 v[84:87], v[236:237], off offset:1024
	s_waitcnt vmcnt(19)
	v_mfma_f32_32x32x16_bf16 v[32:47], v[88:91], v[100:103], v[32:47]
	s_waitcnt vmcnt(18)
	v_mfma_f32_32x32x16_bf16 v[32:47], v[52:55], v[108:111], v[32:47]
	global_load_dwordx4 v[52:55], v[236:237], off offset:2048
	v_mfma_f32_32x32x16_bf16 v[16:31], v[120:123], v[112:115], v[16:31]
	s_waitcnt vmcnt(18)
	v_mfma_f32_32x32x16_bf16 v[32:47], v[92:95], v[112:115], v[32:47]
	s_nop 9
	v_mul_f32_e64 v6, v126, v22
	v_mul_f32_e64 v7, v127, v23
	v_mul_f32_e64 v4, v124, v20
	v_mul_f32_e64 v5, v125, v21
	v_add_co_u32_e32 v124, vcc, s14, v170
	s_mov_b32 s14, 0xa000
	s_nop 0
	v_addc_co_u32_e32 v125, vcc, 0, v171, vcc
	v_add_co_u32_e32 v126, vcc, s14, v170
	s_mov_b32 s14, 0xb000
	s_nop 0
	v_addc_co_u32_e32 v127, vcc, 0, v171, vcc
	s_waitcnt vmcnt(17)
	v_pk_mul_f32 v[14:15], v[58:59], v[30:31]
	v_pk_mul_f32 v[12:13], v[56:57], v[28:29]
	global_load_dwordx4 v[56:59], v[176:177], off
	s_waitcnt vmcnt(17)
	v_pk_mul_f32 v[10:11], v[62:63], v[26:27]
	v_pk_mul_f32 v[8:9], v[60:61], v[24:25]
	s_waitcnt vmcnt(15)
	v_pk_mul_f32 v[2:3], v[78:79], v[18:19]
	v_pk_mul_f32 v[0:1], v[76:77], v[16:17]
	s_waitcnt vmcnt(6)
	v_pk_mul_f32 v[26:27], v[66:67], v[42:43]
	v_mfma_f32_32x32x16_bf16 v[0:15], v[72:75], v[96:99], v[0:15]
	global_load_dwordx4 v[60:63], v[236:237], off offset:3072
	global_load_dwordx4 v[72:75], v[176:177], off offset:96
	global_load_dwordx4 v[76:79], v[176:177], off offset:32
	global_load_dwordx4 v[88:91], v[176:177], off offset:64
	s_waitcnt vmcnt(9)
	v_pk_mul_f32 v[30:31], v[118:119], v[46:47]
	v_pk_mul_f32 v[28:29], v[116:117], v[44:45]
	v_pk_mul_f32 v[24:25], v[64:65], v[40:41]
	s_waitcnt vmcnt(8)
	v_pk_mul_f32 v[22:23], v[70:71], v[38:39]
	v_pk_mul_f32 v[20:21], v[68:69], v[36:37]
	s_waitcnt vmcnt(7)
	v_pk_mul_f32 v[18:19], v[82:83], v[34:35]
	v_pk_mul_f32 v[16:17], v[80:81], v[32:33]
	global_load_dwordx4 v[92:95], v[238:239], off offset:-4096
	global_load_dwordx4 v[100:103], v[168:169], off
	v_mfma_f32_32x32x16_bf16 v[16:31], v[140:143], v[96:99], v[16:31]
	global_load_dwordx4 v[108:111], v[238:239], off offset:-3072
	global_load_dwordx4 v[112:115], v[168:169], off offset:1024
	global_load_dwordx4 v[120:123], v[238:239], off offset:-2048
	global_load_dwordx4 v[32:35], v[168:169], off offset:2048
	global_load_dwordx4 v[36:39], v[238:239], off offset:-1024
	global_load_dwordx4 v[40:43], v[168:169], off offset:3072
	v_lshl_add_u64 v[168:169], v[168:169], 0, s[20:21]
	global_load_dwordx4 v[44:47], v[176:177], off offset:224
	global_load_dwordx4 v[64:67], v[176:177], off offset:192
	global_load_dwordx4 v[68:71], v[176:177], off offset:160
	global_load_dwordx4 v[80:83], v[238:239], off
	s_waitcnt vmcnt(18)
	v_mfma_f32_32x32x16_bf16 v[16:31], v[84:87], v[104:107], v[16:31]
	v_mfma_f32_32x32x16_bf16 v[0:15], v[128:131], v[104:107], v[0:15]
	s_waitcnt vmcnt(17)
	v_mfma_f32_32x32x16_bf16 v[16:31], v[52:55], v[148:151], v[16:31]
	global_load_dwordx4 v[52:55], v[176:177], off offset:128
	global_load_dwordx4 v[84:87], v[238:239], off offset:1024
	v_mfma_f32_32x32x16_bf16 v[0:15], v[132:135], v[148:151], v[0:15]
	v_mfma_f32_32x32x16_bf16 v[0:15], v[136:139], v[144:147], v[0:15]
	s_waitcnt vmcnt(17)
	v_mfma_f32_32x32x16_bf16 v[16:31], v[60:63], v[144:147], v[16:31]
	s_waitcnt vmcnt(16)
	s_nop 8
	v_mul_f32_e64 v14, v74, v14
	v_mul_f32_e64 v15, v75, v15
	v_mul_f32_e64 v12, v72, v12
	v_mul_f32_e64 v13, v73, v13
	v_pk_mul_f32 v[2:3], v[58:59], v[2:3]
	v_pk_mul_f32 v[0:1], v[56:57], v[0:1]
	global_load_dwordx4 v[56:59], v[238:239], off offset:2048
	global_load_dwordx4 v[60:63], v[238:239], off offset:3072
	global_load_dwordx4 v[72:75], v[240:241], off offset:-4096
	s_waitcnt vmcnt(17)
	v_pk_mul_f32 v[10:11], v[90:91], v[10:11]
	v_pk_mul_f32 v[8:9], v[88:89], v[8:9]
	v_pk_mul_f32 v[6:7], v[78:79], v[6:7]
	v_pk_mul_f32 v[4:5], v[76:77], v[4:5]
	s_waitcnt vmcnt(8)
	v_pk_mul_f32 v[30:31], v[46:47], v[30:31]
	v_mfma_f32_32x32x16_bf16 v[0:15], v[92:95], v[100:103], v[0:15]
	v_mul_f32_e64 v28, v44, v28
	v_mul_f32_e64 v29, v45, v29
	s_waitcnt vmcnt(7)
	v_mul_f32_e64 v26, v66, v26
	v_mul_f32_e64 v27, v67, v27
	v_pk_mul_f32 v[24:25], v[64:65], v[24:25]
	s_waitcnt vmcnt(6)
	v_pk_mul_f32 v[22:23], v[70:71], v[22:23]
	v_pk_mul_f32 v[20:21], v[68:69], v[20:21]
	global_load_dwordx4 v[76:79], v[124:125], off offset:96
	global_load_dwordx4 v[88:91], v[124:125], off offset:32
	global_load_dwordx4 v[92:95], v[124:125], off offset:64
	global_load_dwordx4 v[96:99], v[126:127], off offset:-4096
	v_mfma_f32_32x32x16_bf16 v[0:15], v[108:111], v[112:115], v[0:15]
	s_waitcnt vmcnt(8)
	v_mul_f32_e64 v18, v54, v18
	v_mul_f32_e64 v19, v55, v19
	v_mul_f32_e64 v16, v52, v16
	v_mul_f32_e64 v17, v53, v17
	v_mfma_f32_32x32x16_bf16 v[0:15], v[120:123], v[32:35], v[0:15]
	global_load_dwordx4 v[104:107], v[168:169], off
	global_load_dwordx4 v[108:111], v[240:241], off offset:-3072
	global_load_dwordx4 v[116:119], v[168:169], off offset:1024
	global_load_dwordx4 v[120:123], v[240:241], off offset:-2048
	v_mfma_f32_32x32x16_bf16 v[16:31], v[80:83], v[100:103], v[16:31]
	s_waitcnt vmcnt(11)
	v_mfma_f32_32x32x16_bf16 v[16:31], v[84:87], v[112:115], v[16:31]
	v_mfma_f32_32x32x16_bf16 v[0:15], v[36:39], v[40:43], v[0:15]
	global_load_dwordx4 v[36:39], v[168:169], off offset:2048
	global_load_dwordx4 v[44:47], v[240:241], off offset:-1024
	global_load_dwordx4 v[52:55], v[168:169], off offset:3072
	v_lshl_add_u64 v[168:169], v[168:169], 0, s[20:21]
	global_load_dwordx4 v[64:67], v[124:125], off offset:224
	global_load_dwordx4 v[68:71], v[124:125], off offset:192
	global_load_dwordx4 v[80:83], v[124:125], off offset:160
	global_load_dwordx4 v[84:87], v[240:241], off
	s_waitcnt vmcnt(14)
	s_nop 3
	v_pk_mul_f32 v[14:15], v[78:79], v[14:15]
	v_mfma_f32_32x32x16_bf16 v[16:31], v[56:59], v[32:35], v[16:31]
	global_load_dwordx4 v[32:35], v[124:125], off offset:128
	global_load_dwordx4 v[56:59], v[240:241], off offset:1024
	v_mul_f32_e64 v12, v76, v12
	v_mul_f32_e64 v13, v77, v13
	s_waitcnt vmcnt(14)
	v_pk_mul_f32 v[10:11], v[94:95], v[10:11]
	v_pk_mul_f32 v[8:9], v[92:93], v[8:9]
	v_pk_mul_f32 v[6:7], v[90:91], v[6:7]
	v_pk_mul_f32 v[4:5], v[88:89], v[4:5]
	s_waitcnt vmcnt(13)
	v_pk_mul_f32 v[2:3], v[98:99], v[2:3]
	v_mfma_f32_32x32x16_bf16 v[16:31], v[60:63], v[40:43], v[16:31]
	global_load_dwordx4 v[40:43], v[240:241], off offset:2048
	global_load_dwordx4 v[60:63], v[240:241], off offset:3072
	v_mul_f32_e64 v0, v96, v0
	v_mul_f32_e64 v1, v97, v1
	s_waitcnt vmcnt(14)
	s_nop 0
	v_mfma_f32_32x32x16_bf16 v[0:15], v[72:75], v[104:107], v[0:15]
	global_load_dwordx4 v[72:75], v[126:127], off offset:96
	global_load_dwordx4 v[76:79], v[126:127], off offset:64
	global_load_dwordx4 v[88:91], v[244:245], off offset:-4096
	global_load_dwordx4 v[92:95], v[126:127], off offset:32
	global_load_dwordx4 v[96:99], v[126:127], off
	s_waitcnt vmcnt(12)
	v_pk_mul_f32 v[30:31], v[66:67], v[30:31]
	v_pk_mul_f32 v[28:29], v[64:65], v[28:29]
	s_waitcnt vmcnt(11)
	v_pk_mul_f32 v[26:27], v[70:71], v[26:27]
	v_pk_mul_f32 v[24:25], v[68:69], v[24:25]
	s_waitcnt vmcnt(10)
	v_pk_mul_f32 v[22:23], v[82:83], v[22:23]
	v_pk_mul_f32 v[20:21], v[80:81], v[20:21]
	v_mfma_f32_32x32x16_bf16 v[0:15], v[108:111], v[116:119], v[0:15]
	global_load_dwordx4 v[100:103], v[168:169], off
	global_load_dwordx4 v[108:111], v[168:169], off offset:1024
	global_load_dwordx4 v[112:115], v[244:245], off offset:-3072
	s_waitcnt vmcnt(11)
	v_mul_f32_e64 v18, v34, v18
	v_mul_f32_e64 v19, v35, v19
	v_pk_mul_f32 v[16:17], v[32:33], v[16:17]
	v_mfma_f32_32x32x16_bf16 v[0:15], v[120:123], v[36:39], v[0:15]
	v_add_co_u32_e32 v120, vcc, s14, v170
	s_mov_b32 s14, 0xc000
	s_nop 0
	v_addc_co_u32_e32 v121, vcc, 0, v171, vcc
	v_add_co_u32_e32 v124, vcc, s14, v170
	v_mfma_f32_32x32x16_bf16 v[16:31], v[84:87], v[104:107], v[16:31]
	s_nop 0
	v_addc_co_u32_e32 v125, vcc, 0, v171, vcc
	s_mov_b32 s14, 0xd000
	s_waitcnt vmcnt(10)
	v_mfma_f32_32x32x16_bf16 v[16:31], v[56:59], v[116:119], v[16:31]
	v_mfma_f32_32x32x16_bf16 v[0:15], v[44:47], v[52:55], v[0:15]
	global_load_dwordx4 v[44:47], v[120:121], off offset:32
	global_load_dwordx4 v[32:35], v[244:245], off offset:-2048
	global_load_dwordx4 v[64:67], v[168:169], off offset:2048
	global_load_dwordx4 v[56:59], v[244:245], off offset:-1024
	global_load_dwordx4 v[68:71], v[168:169], off offset:3072
	v_lshl_add_u64 v[168:169], v[168:169], 0, s[20:21]
	global_load_dwordx4 v[80:83], v[126:127], off offset:224
	global_load_dwordx4 v[84:87], v[126:127], off offset:192
	global_load_dwordx4 v[104:107], v[244:245], off
	s_waitcnt vmcnt(15)
	s_nop 2
	v_pk_mul_f32 v[14:15], v[74:75], v[14:15]
	v_mfma_f32_32x32x16_bf16 v[16:31], v[40:43], v[36:39], v[16:31]
	global_load_dwordx4 v[36:39], v[126:127], off offset:160
	global_load_dwordx4 v[40:43], v[126:127], off offset:128
	global_load_dwordx4 v[116:119], v[244:245], off offset:1024
	v_mul_f32_e64 v12, v72, v12
	v_mul_f32_e64 v13, v73, v13
	s_waitcnt vmcnt(17)
	v_pk_mul_f32 v[10:11], v[78:79], v[10:11]
	v_pk_mul_f32 v[8:9], v[76:77], v[8:9]
	s_waitcnt vmcnt(15)
	v_pk_mul_f32 v[6:7], v[94:95], v[6:7]
	v_pk_mul_f32 v[4:5], v[92:93], v[4:5]
	s_waitcnt vmcnt(14)
	v_pk_mul_f32 v[2:3], v[98:99], v[2:3]
	v_mfma_f32_32x32x16_bf16 v[16:31], v[60:63], v[52:55], v[16:31]
	global_load_dwordx4 v[52:55], v[244:245], off offset:2048
	global_load_dwordx4 v[60:63], v[244:245], off offset:3072
	v_mul_f32_e64 v0, v96, v0
	v_mul_f32_e64 v1, v97, v1
	s_waitcnt vmcnt(15)
	s_nop 0
	v_mfma_f32_32x32x16_bf16 v[0:15], v[88:91], v[100:103], v[0:15]
	global_load_dwordx4 v[72:75], v[120:121], off offset:96
	global_load_dwordx4 v[76:79], v[120:121], off offset:64
	global_load_dwordx4 v[88:91], v[246:247], off offset:-4096
	global_load_dwordx4 v[92:95], v[124:125], off offset:-4096
	s_waitcnt vmcnt(11)
	v_pk_mul_f32 v[30:31], v[82:83], v[30:31]
	v_mfma_f32_32x32x16_bf16 v[0:15], v[112:115], v[108:111], v[0:15]
	v_mul_f32_e64 v28, v80, v28
	v_mul_f32_e64 v29, v81, v29
	s_waitcnt vmcnt(10)
	v_mul_f32_e64 v26, v86, v26
	v_mul_f32_e64 v27, v87, v27
	v_pk_mul_f32 v[24:25], v[84:85], v[24:25]
	s_waitcnt vmcnt(8)
	v_pk_mul_f32 v[22:23], v[38:39], v[22:23]
	v_pk_mul_f32 v[20:21], v[36:37], v[20:21]
	s_waitcnt vmcnt(7)
	v_pk_mul_f32 v[18:19], v[42:43], v[18:19]
	v_pk_mul_f32 v[16:17], v[40:41], v[16:17]
	v_mfma_f32_32x32x16_bf16 v[0:15], v[32:35], v[64:67], v[0:15]
	global_load_dwordx4 v[32:35], v[168:169], off
	global_load_dwordx4 v[96:99], v[246:247], off offset:-3072
	global_load_dwordx4 v[112:115], v[168:169], off offset:1024
	global_load_dwordx4 v[36:39], v[246:247], off offset:-2048
	global_load_dwordx4 v[40:43], v[168:169], off offset:2048
	v_mfma_f32_32x32x16_bf16 v[16:31], v[104:107], v[100:103], v[16:31]
	s_waitcnt vmcnt(11)
	v_mfma_f32_32x32x16_bf16 v[16:31], v[116:119], v[108:111], v[16:31]
	v_mfma_f32_32x32x16_bf16 v[0:15], v[56:59], v[68:71], v[0:15]
	global_load_dwordx4 v[56:59], v[246:247], off offset:-1024
	global_load_dwordx4 v[80:83], v[120:121], off offset:224
	global_load_dwordx4 v[84:87], v[168:169], off offset:3072
	v_lshl_add_u64 v[168:169], v[168:169], 0, s[20:21]
	global_load_dwordx4 v[100:103], v[120:121], off offset:192
	global_load_dwordx4 v[104:107], v[246:247], off
	global_load_dwordx4 v[108:111], v[120:121], off offset:160
	s_nop 5
	v_pk_mul_f32 v[6:7], v[46:47], v[6:7]
	s_waitcnt vmcnt(16)
	v_mfma_f32_32x32x16_bf16 v[16:31], v[52:55], v[64:67], v[16:31]
	global_load_dwordx4 v[52:55], v[120:121], off offset:128
	global_load_dwordx4 v[64:67], v[246:247], off offset:1024
	v_mul_f32_e64 v4, v44, v4
	v_mul_f32_e64 v5, v45, v5
	global_load_dwordx4 v[44:47], v[124:125], off
	s_waitcnt vmcnt(17)
	v_pk_mul_f32 v[14:15], v[74:75], v[14:15]
	v_pk_mul_f32 v[12:13], v[72:73], v[12:13]
	s_waitcnt vmcnt(16)
	v_pk_mul_f32 v[10:11], v[78:79], v[10:11]
	v_pk_mul_f32 v[8:9], v[76:77], v[8:9]
	v_mfma_f32_32x32x16_bf16 v[16:31], v[60:63], v[68:71], v[16:31]
	global_load_dwordx4 v[60:63], v[246:247], off offset:2048
	global_load_dwordx4 v[68:71], v[246:247], off offset:3072
	s_waitcnt vmcnt(16)
	v_mul_f32_e64 v2, v94, v2
	v_mul_f32_e64 v3, v95, v3
	v_pk_mul_f32 v[0:1], v[92:93], v[0:1]
	s_waitcnt vmcnt(15)
	s_nop 0
	v_mfma_f32_32x32x16_bf16 v[0:15], v[88:91], v[32:35], v[0:15]
	global_load_dwordx4 v[72:75], v[124:125], off offset:96
	global_load_dwordx4 v[76:79], v[124:125], off offset:64
	global_load_dwordx4 v[88:91], v[124:125], off offset:32
	global_load_dwordx4 v[92:95], v[248:249], off offset:-4096
	s_waitcnt vmcnt(13)
	v_pk_mul_f32 v[30:31], v[82:83], v[30:31]
	v_mfma_f32_32x32x16_bf16 v[0:15], v[96:99], v[112:115], v[0:15]
	v_mul_f32_e64 v28, v80, v28
	v_mul_f32_e64 v29, v81, v29
	s_waitcnt vmcnt(11)
	v_mul_f32_e64 v26, v102, v26
	v_mul_f32_e64 v27, v103, v27
	v_pk_mul_f32 v[24:25], v[100:101], v[24:25]
	s_waitcnt vmcnt(9)
	v_pk_mul_f32 v[22:23], v[110:111], v[22:23]
	v_pk_mul_f32 v[20:21], v[108:109], v[20:21]
	s_waitcnt vmcnt(8)
	v_pk_mul_f32 v[18:19], v[54:55], v[18:19]
	v_pk_mul_f32 v[16:17], v[52:53], v[16:17]
	v_mfma_f32_32x32x16_bf16 v[0:15], v[36:39], v[40:43], v[0:15]
	global_load_dwordx4 v[36:39], v[168:169], off
	global_load_dwordx4 v[96:99], v[168:169], off offset:1024
	global_load_dwordx4 v[116:119], v[248:249], off offset:-3072
	global_load_dwordx4 v[120:123], v[248:249], off offset:-2048
	v_mfma_f32_32x32x16_bf16 v[16:31], v[104:107], v[32:35], v[16:31]
	global_load_dwordx4 v[32:35], v[168:169], off offset:2048
	s_waitcnt vmcnt(12)
	v_mfma_f32_32x32x16_bf16 v[16:31], v[64:67], v[112:115], v[16:31]
	v_mfma_f32_32x32x16_bf16 v[0:15], v[56:59], v[84:87], v[0:15]
	global_load_dwordx4 v[52:55], v[248:249], off offset:-1024
	global_load_dwordx4 v[56:59], v[124:125], off offset:224
	global_load_dwordx4 v[64:67], v[168:169], off offset:3072
	v_lshl_add_u64 v[168:169], v[168:169], 0, s[20:21]
	global_load_dwordx4 v[80:83], v[124:125], off offset:192
	global_load_dwordx4 v[100:103], v[124:125], off offset:160
	global_load_dwordx4 v[104:107], v[248:249], off
	s_waitcnt vmcnt(17)
	s_nop 4
	v_pk_mul_f32 v[2:3], v[46:47], v[2:3]
	s_waitcnt vmcnt(16)
	v_mfma_f32_32x32x16_bf16 v[16:31], v[60:63], v[40:43], v[16:31]
	global_load_dwordx4 v[40:43], v[124:125], off offset:128
	global_load_dwordx4 v[60:63], v[248:249], off offset:1024
	global_load_dwordx4 v[108:111], v[248:249], off offset:2048
	v_mul_f32_e64 v0, v44, v0
	v_mul_f32_e64 v1, v45, v1
	v_add_co_u32_e32 v124, vcc, s14, v170
	s_mov_b32 s14, 0xe000
	s_nop 0
	v_addc_co_u32_e32 v125, vcc, 0, v171, vcc
	s_waitcnt vmcnt(18)
	v_mfma_f32_32x32x16_bf16 v[16:31], v[68:71], v[84:87], v[16:31]
	global_load_dwordx4 v[44:47], v[248:249], off offset:3072
	global_load_dwordx4 v[68:71], v[250:251], off offset:-4096
	s_waitcnt vmcnt(19)
	v_mul_f32_e64 v14, v74, v14
	v_mul_f32_e64 v15, v75, v15
	v_pk_mul_f32 v[12:13], v[72:73], v[12:13]
	s_waitcnt vmcnt(18)
	v_pk_mul_f32 v[10:11], v[78:79], v[10:11]
	v_pk_mul_f32 v[8:9], v[76:77], v[8:9]
	s_waitcnt vmcnt(17)
	v_pk_mul_f32 v[6:7], v[90:91], v[6:7]
	v_pk_mul_f32 v[4:5], v[88:89], v[4:5]
	v_add_co_u32_e32 v126, vcc, s14, v170
	s_waitcnt vmcnt(15)
	v_mfma_f32_32x32x16_bf16 v[0:15], v[92:95], v[36:39], v[0:15]
	v_addc_co_u32_e32 v127, vcc, 0, v171, vcc
	global_load_dwordx4 v[72:75], v[124:125], off offset:96
	global_load_dwordx4 v[76:79], v[124:125], off offset:32
	global_load_dwordx4 v[84:87], v[124:125], off offset:64
	global_load_dwordx4 v[88:91], v[126:127], off offset:-4096
	s_or_b32 s14, s1, s0
	s_ashr_i32 s15, s14, 31
	s_waitcnt vmcnt(17)
	v_mfma_f32_32x32x16_bf16 v[0:15], v[116:119], v[96:99], v[0:15]
	global_load_dwordx4 v[92:95], v[168:169], off
	global_load_dwordx4 v[112:115], v[250:251], off offset:-3072
	global_load_dwordx4 v[116:119], v[168:169], off offset:1024
	s_lshl_b64 s[14:15], s[14:15], 15
	s_cmp_lg_u32 s0, 0
	s_waitcnt vmcnt(16)
	v_pk_mul_f32 v[30:31], v[58:59], v[30:31]
	v_pk_mul_f32 v[28:29], v[56:57], v[28:29]
	s_waitcnt vmcnt(14)
	v_pk_mul_f32 v[26:27], v[82:83], v[26:27]
	v_pk_mul_f32 v[24:25], v[80:81], v[24:25]
	s_waitcnt vmcnt(13)
	v_pk_mul_f32 v[22:23], v[102:103], v[22:23]
	v_pk_mul_f32 v[20:21], v[100:101], v[20:21]
	v_mfma_f32_32x32x16_bf16 v[0:15], v[120:123], v[32:35], v[0:15]
	s_waitcnt vmcnt(11)
	v_mul_f32_e64 v18, v42, v18
	v_mul_f32_e64 v19, v43, v19
	v_mul_f32_e64 v16, v40, v16
	v_mul_f32_e64 v17, v41, v17
	v_mfma_f32_32x32x16_bf16 v[0:15], v[52:55], v[64:67], v[0:15]
	s_nop 0
	v_mfma_f32_32x32x16_bf16 v[16:31], v[104:107], v[36:39], v[16:31]
	global_load_dwordx4 v[36:39], v[250:251], off offset:-2048
	global_load_dwordx4 v[40:43], v[168:169], off offset:2048
	global_load_dwordx4 v[52:55], v[250:251], off offset:-1024
	s_waitcnt vmcnt(9)
	s_nop 5
	v_mul_f32_e64 v14, v74, v14
	v_mul_f32_e64 v15, v75, v15
	v_mfma_f32_32x32x16_bf16 v[16:31], v[60:63], v[96:99], v[16:31]
	global_load_dwordx4 v[56:59], v[124:125], off offset:224
	global_load_dwordx4 v[60:63], v[168:169], off offset:3072
	v_lshl_add_u64 v[168:169], v[168:169], 0, s[20:21]
	global_load_dwordx4 v[80:83], v[124:125], off offset:192
	global_load_dwordx4 v[96:99], v[124:125], off offset:160
	global_load_dwordx4 v[100:103], v[250:251], off
	v_pk_mul_f32 v[12:13], v[72:73], v[12:13]
	s_waitcnt vmcnt(12)
	v_pk_mul_f32 v[10:11], v[86:87], v[10:11]
	v_pk_mul_f32 v[8:9], v[84:85], v[8:9]
	v_pk_mul_f32 v[6:7], v[78:79], v[6:7]
	v_pk_mul_f32 v[4:5], v[76:77], v[4:5]
	s_waitcnt vmcnt(11)
	v_pk_mul_f32 v[2:3], v[90:91], v[2:3]
	v_mfma_f32_32x32x16_bf16 v[16:31], v[108:111], v[32:35], v[16:31]
	global_load_dwordx4 v[32:35], v[124:125], off offset:128
	global_load_dwordx4 v[104:107], v[250:251], off offset:1024
	v_mul_f32_e64 v0, v88, v0
	v_mul_f32_e64 v1, v89, v1
	v_mfma_f32_32x32x16_bf16 v[16:31], v[44:47], v[64:67], v[16:31]
	global_load_dwordx4 v[44:47], v[250:251], off offset:2048
	global_load_dwordx4 v[64:67], v[250:251], off offset:3072
	s_waitcnt vmcnt(14)
	v_mfma_f32_32x32x16_bf16 v[0:15], v[68:71], v[92:95], v[0:15]
	global_load_dwordx4 v[68:71], v[126:127], off offset:96
	global_load_dwordx4 v[72:75], v[126:127], off offset:64
	global_load_dwordx4 v[76:79], v[252:253], off offset:-4096
	global_load_dwordx4 v[84:87], v[126:127], off offset:32
	global_load_dwordx4 v[88:91], v[126:127], off
	s_waitcnt vmcnt(13)
	s_nop 1
	v_pk_mul_f32 v[30:31], v[58:59], v[30:31]
	v_mfma_f32_32x32x16_bf16 v[0:15], v[112:115], v[116:119], v[0:15]
	v_mul_f32_e64 v28, v56, v28
	v_mul_f32_e64 v29, v57, v29
	s_waitcnt vmcnt(11)
	v_mul_f32_e64 v26, v82, v26
	v_mul_f32_e64 v27, v83, v27
	v_pk_mul_f32 v[24:25], v[80:81], v[24:25]
	s_waitcnt vmcnt(10)
	v_pk_mul_f32 v[22:23], v[98:99], v[22:23]
	v_pk_mul_f32 v[20:21], v[96:97], v[20:21]
	s_waitcnt vmcnt(8)
	v_pk_mul_f32 v[18:19], v[34:35], v[18:19]
	v_pk_mul_f32 v[16:17], v[32:33], v[16:17]
	v_mfma_f32_32x32x16_bf16 v[0:15], v[36:39], v[40:43], v[0:15]
	global_load_dwordx4 v[36:39], v[168:169], off
	global_load_dwordx4 v[108:111], v[252:253], off offset:-3072
	global_load_dwordx4 v[112:115], v[168:169], off offset:1024
	global_load_dwordx4 v[120:123], v[172:173], off
	global_load_dwordx4 v[32:35], v[168:169], off offset:2048
	v_mfma_f32_32x32x16_bf16 v[16:31], v[100:103], v[92:95], v[16:31]
	s_waitcnt vmcnt(12)
	v_mfma_f32_32x32x16_bf16 v[16:31], v[104:107], v[116:119], v[16:31]
	v_mfma_f32_32x32x16_bf16 v[0:15], v[52:55], v[60:63], v[0:15]
	global_load_dwordx4 v[52:55], v[252:253], off offset:-2048
	global_load_dwordx4 v[56:59], v[252:253], off offset:-1024
	global_load_dwordx4 v[80:83], v[126:127], off offset:224
	global_load_dwordx4 v[92:95], v[168:169], off offset:3072
	global_load_dwordx4 v[96:99], v[126:127], off offset:192
	global_load_dwordx4 v[100:103], v[126:127], off offset:160
	global_load_dwordx4 v[104:107], v[252:253], off
	s_waitcnt vmcnt(16)
	s_nop 3
	v_pk_mul_f32 v[14:15], v[14:15], v[70:71]
	v_mfma_f32_32x32x16_bf16 v[16:31], v[44:47], v[40:43], v[16:31]
	global_load_dwordx4 v[40:43], v[126:127], off offset:128
	v_mul_f32_e64 v12, v12, v68
	v_mul_f32_e64 v13, v13, v69
	s_waitcnt vmcnt(16)
	v_mul_f32_e64 v10, v10, v74
	v_mul_f32_e64 v11, v11, v75
	v_pk_mul_f32 v[8:9], v[8:9], v[72:73]
	s_waitcnt vmcnt(14)
	v_pk_mul_f32 v[6:7], v[6:7], v[86:87]
	v_pk_mul_f32 v[4:5], v[4:5], v[84:85]
	s_waitcnt vmcnt(13)
	v_pk_mul_f32 v[2:3], v[2:3], v[90:91]
	v_mfma_f32_32x32x16_bf16 v[16:31], v[64:67], v[60:63], v[16:31]
	global_load_dwordx4 v[44:47], v[252:253], off offset:1024
	global_load_dwordx4 v[60:63], v[172:173], off offset:32
	v_mul_f32_e64 v0, v0, v88
	v_mul_f32_e64 v1, v1, v89
	global_load_dwordx4 v[64:67], v[252:253], off offset:2048
	global_load_dwordx4 v[68:71], v[172:173], off offset:64
	global_load_dwordx4 v[72:75], v[252:253], off offset:3072
	s_waitcnt vmcnt(10)
	s_nop 3
	v_pk_mul_f32 v[30:31], v[30:31], v[82:83]
	v_mfma_f32_32x32x16_bf16 v[0:15], v[76:79], v[36:39], v[0:15]
	v_mul_f32_e64 v28, v28, v80
	v_mul_f32_e64 v29, v29, v81
	s_waitcnt vmcnt(8)
	v_mul_f32_e64 v26, v26, v98
	v_mul_f32_e64 v27, v27, v99
	v_pk_mul_f32 v[24:25], v[24:25], v[96:97]
	s_waitcnt vmcnt(7)
	v_pk_mul_f32 v[22:23], v[22:23], v[102:103]
	v_pk_mul_f32 v[20:21], v[20:21], v[100:101]
	s_waitcnt vmcnt(5)
	v_pk_mul_f32 v[18:19], v[18:19], v[42:43]
	v_mfma_f32_32x32x16_bf16 v[0:15], v[108:111], v[112:115], v[0:15]
	v_mul_f32_e64 v16, v16, v40
	v_mul_f32_e64 v17, v17, v41
	v_mfma_f32_32x32x16_bf16 v[0:15], v[52:55], v[32:35], v[0:15]
	global_load_dwordx4 v[52:55], v[172:173], off offset:96
	global_load_dwordx4 v[76:79], v[172:173], off offset:128
	global_load_dwordx4 v[84:87], v[172:173], off offset:160
	v_mfma_f32_32x32x16_bf16 v[16:31], v[104:107], v[36:39], v[16:31]
	global_load_dwordx4 v[36:39], v[172:173], off offset:192
	s_waitcnt vmcnt(8)
	v_mfma_f32_32x32x16_bf16 v[16:31], v[44:47], v[112:115], v[16:31]
	s_waitcnt vmcnt(6)
	v_mfma_f32_32x32x16_bf16 v[16:31], v[64:67], v[32:35], v[16:31]
	v_mfma_f32_32x32x16_bf16 v[0:15], v[56:59], v[92:95], v[0:15]
	s_waitcnt vmcnt(4)
	v_mfma_f32_32x32x16_bf16 v[16:31], v[72:75], v[92:95], v[16:31]
	s_nop 9
	v_mul_f32_e32 v40, v120, v0
	v_mul_f32_e32 v41, v121, v1
	v_lshl_add_u64 v[0:1], v[156:157], 0, s[14:15]
	v_mul_f32_e32 v2, v122, v2
	v_mul_f32_e32 v3, v123, v3
	v_mul_f32_e32 v4, v60, v4
	v_mul_f32_e32 v5, v61, v5
	v_mul_f32_e32 v6, v62, v6
	v_mul_f32_e32 v7, v63, v7
	v_mul_f32_e32 v8, v68, v8
	v_mul_f32_e32 v9, v69, v9
	v_mul_f32_e32 v10, v70, v10
	v_mul_f32_e32 v11, v71, v11
	v_mul_f32_e32 v31, v51, v31
	v_mul_f32_e32 v28, v48, v28
	v_mul_f32_e32 v29, v49, v29
	v_mul_f32_e32 v30, v50, v30
	s_waitcnt vmcnt(3)
	v_mul_f32_e32 v12, v52, v12
	v_mul_f32_e32 v13, v53, v13
	v_mul_f32_e32 v14, v54, v14
	v_mul_f32_e32 v15, v55, v15
	global_store_dword v[0:1], v40, off
	global_store_dword v[0:1], v41, off offset:256
	global_store_dword v[0:1], v2, off offset:512
	global_store_dword v[0:1], v3, off offset:768
	global_store_dword v[0:1], v4, off offset:1024
	global_store_dword v[0:1], v5, off offset:1280
	global_store_dword v[0:1], v6, off offset:1536
	global_store_dword v[0:1], v7, off offset:1792
	global_store_dword v[0:1], v8, off offset:2048
	global_store_dword v[0:1], v9, off offset:2304
	global_store_dword v[0:1], v10, off offset:2560
	global_store_dword v[0:1], v11, off offset:2816
	global_store_dword v[0:1], v12, off offset:3072
	global_store_dword v[0:1], v13, off offset:3328
	global_store_dword v[0:1], v14, off offset:3584
	global_store_dword v[0:1], v15, off offset:3840
	v_add_co_u32_e32 v0, vcc, s29, v0
	s_waitcnt vmcnt(18)
	v_mul_f32_e32 v16, v76, v16
	v_addc_co_u32_e32 v1, vcc, 0, v1, vcc
	v_mul_f32_e32 v17, v77, v17
	v_mul_f32_e32 v18, v78, v18
	v_mul_f32_e32 v19, v79, v19
	s_waitcnt vmcnt(17)
	v_mul_f32_e32 v20, v84, v20
	v_mul_f32_e32 v21, v85, v21
	v_mul_f32_e32 v22, v86, v22
	v_mul_f32_e32 v23, v87, v23
	s_waitcnt vmcnt(16)
	v_mul_f32_e32 v24, v36, v24
	v_mul_f32_e32 v25, v37, v25
	v_mul_f32_e32 v26, v38, v26
	v_mul_f32_e32 v27, v39, v27
	global_store_dword v[0:1], v16, off
	global_store_dword v[0:1], v17, off offset:256
	global_store_dword v[0:1], v18, off offset:512
	global_store_dword v[0:1], v19, off offset:768
	global_store_dword v[0:1], v20, off offset:1024
	global_store_dword v[0:1], v21, off offset:1280
	global_store_dword v[0:1], v22, off offset:1536
	global_store_dword v[0:1], v23, off offset:1792
	global_store_dword v[0:1], v24, off offset:2048
	global_store_dword v[0:1], v25, off offset:2304
	global_store_dword v[0:1], v26, off offset:2560
	global_store_dword v[0:1], v27, off offset:2816
	global_store_dword v[0:1], v28, off offset:3072
	global_store_dword v[0:1], v29, off offset:3328
	global_store_dword v[0:1], v30, off offset:3584
	global_store_dword v[0:1], v31, off offset:3840
	s_cbranch_scc1 .LBB0_209
	s_lshr_b32 s0, s6, 4
	s_and_b32 s0, s0, 3
	s_lshl_b32 s0, s0, 10
	s_add_u32 s0, s8, s0
	s_addc_u32 s1, s9, 0
	v_lshl_add_u64 v[0:1], v[158:159], 0, s[0:1]
	v_mov_b32_e32 v2, 1.0
	s_mov_b64 s[0:1], 0

.LBB0_243:
	v_add_u32_e32 v203, v198, v200
	v_add_u32_e32 v186, v201, v200
	ds_read_b128 v[244:247], v203 offset:40960
	ds_read_b128 v[248:251], v203 offset:43008
	ds_read_b128 v[206:209], v186 offset:24576
	ds_read_b128 v[210:213], v186 offset:26624
	ds_read_b128 v[214:217], v186 offset:28672
	ds_read_b128 v[238:241], v186 offset:30720
	v_mfma_f32_32x32x16_bf16 v[112:127], v[136:139], v[148:151], v[112:127]
	v_add_u32_e32 v204, v201, v202
	v_add_u32_e32 v205, v198, v202
	v_mfma_f32_32x32x16_bf16 v[96:111], v[132:135], v[148:151], v[96:111]
	v_mfma_f32_32x32x16_bf16 v[80:95], v[136:139], v[144:147], v[80:95]
	v_mfma_f32_32x32x16_bf16 v[64:79], v[132:135], v[144:147], v[64:79]
	v_mfma_f32_32x32x16_bf16 v[48:63], v[136:139], v[140:143], v[48:63]
	v_mfma_f32_32x32x16_bf16 v[32:47], v[132:135], v[140:143], v[32:47]
	v_mfma_f32_32x32x16_bf16 v[16:31], v[136:139], v[128:131], v[16:31]
	v_mfma_f32_32x32x16_bf16 v[0:15], v[132:135], v[128:131], v[0:15]
	ds_read_b128 v[128:131], v204 offset:24576
	ds_read_b128 v[132:135], v204 offset:26624
	ds_read_b128 v[136:139], v204 offset:28672
	ds_read_b128 v[140:143], v204 offset:30720
	ds_read_b128 v[144:147], v205 offset:40960
	ds_read_b128 v[148:151], v205 offset:43008
	s_waitcnt lgkmcnt(9)
	v_mfma_f32_32x32x16_bf16 v[112:127], v[244:247], v[206:209], v[112:127]
	v_mfma_f32_32x32x16_bf16 v[96:111], v[248:251], v[206:209], v[96:111]
	s_waitcnt lgkmcnt(8)
	v_mfma_f32_32x32x16_bf16 v[80:95], v[244:247], v[210:213], v[80:95]
	v_mfma_f32_32x32x16_bf16 v[64:79], v[248:251], v[210:213], v[64:79]
	s_waitcnt lgkmcnt(7)
	v_mfma_f32_32x32x16_bf16 v[48:63], v[244:247], v[214:217], v[48:63]
	v_mfma_f32_32x32x16_bf16 v[32:47], v[248:251], v[214:217], v[32:47]
	s_waitcnt lgkmcnt(6)
	v_mfma_f32_32x32x16_bf16 v[16:31], v[244:247], v[238:241], v[16:31]
	v_mfma_f32_32x32x16_bf16 v[0:15], v[248:251], v[238:241], v[0:15]
	s_waitcnt vmcnt(2)
	ds_write_b128 v199, v[164:167] offset:12288
	v_lshl_add_u64 v[164:165], v[196:197], 0, s[0:1]
	ds_write_b128 v199, v[152:155]
	v_add_co_u32_e32 v152, vcc, s92, v164
	ds_write_b128 v199, v[156:159] offset:4096
	s_nop 0
	v_addc_co_u32_e32 v153, vcc, 0, v165, vcc
	v_add_co_u32_e32 v156, vcc, s93, v164
	ds_write_b128 v199, v[160:163] offset:8192
	s_nop 0
	v_addc_co_u32_e32 v157, vcc, 0, v165, vcc
	v_add_co_u32_e32 v160, vcc, s88, v164
	s_waitcnt vmcnt(0)
	ds_write_b128 v199, v[172:175] offset:20480
	v_addc_co_u32_e32 v161, vcc, 0, v165, vcc
	v_add_co_u32_e32 v164, vcc, s89, v164
	v_lshl_add_u64 v[172:173], v[178:179], 0, s[0:1]
	s_nop 0
	v_addc_co_u32_e32 v165, vcc, 0, v165, vcc
	ds_write_b128 v199, v[168:171] offset:16384
	global_load_dwordx4 v[168:171], v[172:173], off offset:192
	v_add_co_u32_e32 v172, vcc, s78, v172
	global_load_dwordx4 v[152:155], v[152:153], off offset:192
	s_nop 0
	v_addc_co_u32_e32 v173, vcc, 0, v173, vcc
	global_load_dwordx4 v[156:159], v[156:157], off offset:192
	s_nop 0
	global_load_dwordx4 v[160:163], v[160:161], off offset:192
	s_nop 0
	global_load_dwordx4 v[164:167], v[164:165], off offset:192
	s_nop 0
	global_load_dwordx4 v[172:175], v[172:173], off offset:192
	s_waitcnt lgkmcnt(0)
	s_barrier
	ds_read_b128 v[244:247], v203 offset:16384
	ds_read_b128 v[248:251], v203 offset:18432
	ds_read_b128 v[206:209], v186
	ds_read_b128 v[210:213], v186 offset:2048
	ds_read_b128 v[214:217], v186 offset:4096
	ds_read_b128 v[238:241], v186 offset:6144
	v_mfma_f32_32x32x16_bf16 v[112:127], v[144:147], v[128:131], v[112:127]
	v_mfma_f32_32x32x16_bf16 v[96:111], v[148:151], v[128:131], v[96:111]
	v_mfma_f32_32x32x16_bf16 v[80:95], v[144:147], v[132:135], v[80:95]
	v_mfma_f32_32x32x16_bf16 v[64:79], v[148:151], v[132:135], v[64:79]
	v_mfma_f32_32x32x16_bf16 v[48:63], v[144:147], v[136:139], v[48:63]
	v_mfma_f32_32x32x16_bf16 v[32:47], v[148:151], v[136:139], v[32:47]
	v_mfma_f32_32x32x16_bf16 v[16:31], v[144:147], v[140:143], v[16:31]
	v_mfma_f32_32x32x16_bf16 v[0:15], v[148:151], v[140:143], v[0:15]
	ds_read_b128 v[148:151], v204
	ds_read_b128 v[144:147], v204 offset:2048
	ds_read_b128 v[140:143], v204 offset:4096
	ds_read_b128 v[128:131], v204 offset:6144
	ds_read_b128 v[136:139], v205 offset:16384
	ds_read_b128 v[132:135], v205 offset:18432
	s_waitcnt lgkmcnt(9)
	v_mfma_f32_32x32x16_bf16 v[112:127], v[244:247], v[206:209], v[112:127]
	v_mfma_f32_32x32x16_bf16 v[96:111], v[248:251], v[206:209], v[96:111]
	s_waitcnt lgkmcnt(8)
	v_mfma_f32_32x32x16_bf16 v[80:95], v[244:247], v[210:213], v[80:95]
	v_mfma_f32_32x32x16_bf16 v[64:79], v[248:251], v[210:213], v[64:79]
	s_waitcnt lgkmcnt(7)
	v_mfma_f32_32x32x16_bf16 v[48:63], v[244:247], v[214:217], v[48:63]
	v_mfma_f32_32x32x16_bf16 v[32:47], v[248:251], v[214:217], v[32:47]
	s_waitcnt lgkmcnt(6)
	v_mfma_f32_32x32x16_bf16 v[16:31], v[244:247], v[238:241], v[16:31]
	v_mfma_f32_32x32x16_bf16 v[0:15], v[248:251], v[238:241], v[0:15]
	s_min_u32 s7, s6, 60
	s_lshl_b32 s66, s7, 6
	s_add_i32 s8, s66, 0xc0
	s_mov_b32 s9, s67
	s_waitcnt vmcnt(4)
	ds_write_b128 v199, v[152:155] offset:24576
	s_waitcnt vmcnt(3)
	ds_write_b128 v199, v[156:159] offset:28672
	s_waitcnt vmcnt(2)
	ds_write_b128 v199, v[160:163] offset:32768
	s_waitcnt vmcnt(1)
	ds_write_b128 v199, v[164:167] offset:36864
	ds_write_b128 v199, v[168:171] offset:40960
	s_waitcnt vmcnt(0)
	ds_write_b128 v199, v[172:175] offset:45056
	v_lshl_add_u64 v[152:153], v[176:177], 0, s[66:67]
	v_lshl_add_u64 v[156:157], v[180:181], 0, s[8:9]
	v_lshl_add_u64 v[160:161], v[182:183], 0, s[8:9]
	v_lshl_add_u64 v[164:165], v[192:193], 0, s[8:9]
	v_lshl_add_u64 v[168:169], v[178:179], 0, s[66:67]
	v_lshl_add_u64 v[172:173], v[194:195], 0, s[8:9]
	global_load_dwordx4 v[152:155], v[152:153], off offset:192
	s_add_i32 s6, s6, 2
	global_load_dwordx4 v[156:159], v[156:157], off
	s_add_u32 s0, s0, 0x80
	global_load_dwordx4 v[160:163], v[160:161], off
	s_addc_u32 s1, s1, 0
	global_load_dwordx4 v[164:167], v[164:165], off
	s_cmpk_lg_i32 s0, 0xf80
	global_load_dwordx4 v[168:171], v[168:169], off offset:192
	s_nop 0
	global_load_dwordx4 v[172:175], v[172:173], off
	s_waitcnt lgkmcnt(0)
	s_barrier
	s_cbranch_scc1 .LBB0_243
	s_waitcnt vmcnt(1)
	ds_read_b128 v[168:171], v203 offset:40960
	s_waitcnt vmcnt(0)
	ds_read_b128 v[172:175], v203 offset:43008
	ds_read_b128 v[152:155], v186 offset:24576
	ds_read_b128 v[156:159], v186 offset:26624
	ds_read_b128 v[160:163], v186 offset:28672
	ds_read_b128 v[164:167], v186 offset:30720
	v_mfma_f32_32x32x16_bf16 v[112:127], v[136:139], v[148:151], v[112:127]
	v_mfma_f32_32x32x16_bf16 v[96:111], v[132:135], v[148:151], v[96:111]
	v_mfma_f32_32x32x16_bf16 v[80:95], v[136:139], v[144:147], v[80:95]
	v_mfma_f32_32x32x16_bf16 v[64:79], v[132:135], v[144:147], v[64:79]
	v_mfma_f32_32x32x16_bf16 v[48:63], v[136:139], v[140:143], v[48:63]
	v_mfma_f32_32x32x16_bf16 v[32:47], v[132:135], v[140:143], v[32:47]
	v_mfma_f32_32x32x16_bf16 v[16:31], v[136:139], v[128:131], v[16:31]
	v_mfma_f32_32x32x16_bf16 v[0:15], v[132:135], v[128:131], v[0:15]
	ds_read_b128 v[128:131], v204 offset:24576
	ds_read_b128 v[132:135], v204 offset:26624
	ds_read_b128 v[136:139], v204 offset:28672
	ds_read_b128 v[140:143], v204 offset:30720
	ds_read_b128 v[144:147], v205 offset:40960
	ds_read_b128 v[176:179], v205 offset:43008
	s_waitcnt lgkmcnt(9)
	v_mfma_f32_32x32x16_bf16 v[112:127], v[168:171], v[152:155], v[112:127]
	v_mfma_f32_32x32x16_bf16 v[96:111], v[172:175], v[152:155], v[96:111]
	s_waitcnt lgkmcnt(8)
	v_mfma_f32_32x32x16_bf16 v[80:95], v[168:171], v[156:159], v[80:95]
	v_mfma_f32_32x32x16_bf16 v[64:79], v[172:175], v[156:159], v[64:79]
	s_waitcnt lgkmcnt(7)
	v_mfma_f32_32x32x16_bf16 v[48:63], v[168:171], v[160:163], v[48:63]
	v_mfma_f32_32x32x16_bf16 v[32:47], v[172:175], v[160:163], v[32:47]
	s_waitcnt lgkmcnt(6)
	v_mfma_f32_32x32x16_bf16 v[16:31], v[168:171], v[164:167], v[16:31]
	v_mfma_f32_32x32x16_bf16 v[0:15], v[172:175], v[164:167], v[0:15]
	v_mov_b32_e32 v149, v189
	v_mov_b32_e32 v148, v189
	s_waitcnt lgkmcnt(0)
	s_barrier
	v_mfma_f32_32x32x16_bf16 v[112:127], v[144:147], v[128:131], v[112:127]
	s_addk_i32 s4, 0xf800
	v_and_b32_e32 v148, 63, v189
	v_lshrrev_b32_e32 v149, 6, v189
	v_and_b32_e32 v150, 31, v148
	v_lshrrev_b32_e32 v151, 5, v148
	v_lshrrev_b32_e32 v162, 3, v150
	v_mfma_f32_32x32x16_bf16 v[96:111], v[176:179], v[128:131], v[96:111]
	v_lshlrev_b32_e32 v163, 14, v149
	v_lshl_add_u32 v164, v162, 9, v163
	v_lshl_add_u32 v164, v151, 6, v164
	v_and_b32_e32 v165, 7, v150
	v_lshl_add_u32 v164, v165, 1, v164
	v_mfma_f32_32x32x16_bf16 v[80:95], v[144:147], v[132:135], v[80:95]
	v_lshl_add_u32 v166, v162, 4, v164
	v_xor_b32_e32 v165, 1, v162
	v_lshl_add_u32 v167, v165, 4, v164
	v_xor_b32_e32 v165, 2, v162
	v_lshl_add_u32 v168, v165, 4, v164
	v_xor_b32_e32 v165, 3, v162
	v_lshl_add_u32 v169, v165, 4, v164
	v_mfma_f32_32x32x16_bf16 v[64:79], v[176:179], v[132:135], v[64:79]
	v_lshl_add_u32 v164, v151, 9, v163
	v_xor_b32_e32 v165, v150, v151
	v_lshl_add_u32 v170, v165, 4, v164
	v_xor_b32_e32 v165, 2, v165
	v_lshl_add_u32 v171, v165, 4, v164
	v_mfma_f32_32x32x16_bf16 v[48:63], v[144:147], v[136:139], v[48:63]
	v_and_b32_e32 v164, 1, v149
	v_lshl_add_u32 v164, v164, 6, s4
	v_lshrrev_b32_e32 v165, 1, v149
	v_lshlrev_b32_e32 v165, 7, v165
	v_add_u32_e32 v165, s5, v165
	v_mfma_f32_32x32x16_bf16 v[32:47], v[176:179], v[136:139], v[32:47]
	v_lshrrev_b32_e32 v165, 6, v165
	v_lshlrev_b32_e32 v165, 16, v165
	v_lshl_or_b32 v165, v148, 4, v165
	v_bfe_u32 v163, v164, 5, 4
	v_lshl_or_b32 v165, v163, 12, v165
	v_mfma_f32_32x32x16_bf16 v[16:31], v[144:147], v[140:143], v[16:31]
	v_lshrrev_b32_e32 v163, 9, v164
	v_lshl_or_b32 v152, v163, 23, v165
	v_mov_b32_e32 v153, 0
	v_lshl_add_u64 v[152:153], s[16:17], 0, v[152:153]
	v_mfma_f32_32x32x16_bf16 v[0:15], v[176:179], v[140:143], v[0:15]
	v_add_co_u32_e32 v154, vcc, 0x1000, v152
	s_nop 1
	v_addc_co_u32_e32 v155, vcc, 0, v153, vcc
	v_add_co_u32_e32 v156, vcc, 0x10000, v152
	s_nop 1
	v_addc_co_u32_e32 v157, vcc, 0, v153, vcc
	v_add_co_u32_e32 v158, vcc, 0x11000, v152
	s_nop 1
	v_addc_co_u32_e32 v159, vcc, 0, v153, vcc
	v_cvt_pk_bf16_f32 v112, v112, v112
	ds_write_b16 v166, v112
	v_cvt_pk_bf16_f32 v113, v113, v113
	ds_write_b16 v167, v113
	v_cvt_pk_bf16_f32 v114, v114, v114
	ds_write_b16 v168, v114
	v_cvt_pk_bf16_f32 v115, v115, v115
	ds_write_b16 v169, v115
	v_cvt_pk_bf16_f32 v116, v116, v116
	ds_write_b16 v166, v116 offset:128
	v_cvt_pk_bf16_f32 v117, v117, v117
	ds_write_b16 v167, v117 offset:128
	v_cvt_pk_bf16_f32 v118, v118, v118
	ds_write_b16 v168, v118 offset:128
	v_cvt_pk_bf16_f32 v119, v119, v119
	ds_write_b16 v169, v119 offset:128
	v_cvt_pk_bf16_f32 v120, v120, v120
	ds_write_b16 v166, v120 offset:256
	v_cvt_pk_bf16_f32 v121, v121, v121
	ds_write_b16 v167, v121 offset:256
	v_cvt_pk_bf16_f32 v122, v122, v122
	ds_write_b16 v168, v122 offset:256
	v_cvt_pk_bf16_f32 v123, v123, v123
	ds_write_b16 v169, v123 offset:256
	v_cvt_pk_bf16_f32 v124, v124, v124
	ds_write_b16 v166, v124 offset:384
	v_cvt_pk_bf16_f32 v125, v125, v125
	ds_write_b16 v167, v125 offset:384
	v_cvt_pk_bf16_f32 v126, v126, v126
	ds_write_b16 v168, v126 offset:384
	v_cvt_pk_bf16_f32 v127, v127, v127
	ds_write_b16 v169, v127 offset:384
	v_cvt_pk_bf16_f32 v96, v96, v96
	ds_write_b16 v166, v96 offset:4096
	v_cvt_pk_bf16_f32 v97, v97, v97
	ds_write_b16 v167, v97 offset:4096
	v_cvt_pk_bf16_f32 v98, v98, v98
	ds_write_b16 v168, v98 offset:4096
	v_cvt_pk_bf16_f32 v99, v99, v99
	ds_write_b16 v169, v99 offset:4096
	v_cvt_pk_bf16_f32 v100, v100, v100
	ds_write_b16 v166, v100 offset:4224
	v_cvt_pk_bf16_f32 v101, v101, v101
	ds_write_b16 v167, v101 offset:4224
	v_cvt_pk_bf16_f32 v102, v102, v102
	ds_write_b16 v168, v102 offset:4224
	v_cvt_pk_bf16_f32 v103, v103, v103
	ds_write_b16 v169, v103 offset:4224
	v_cvt_pk_bf16_f32 v104, v104, v104
	ds_write_b16 v166, v104 offset:4352
	v_cvt_pk_bf16_f32 v105, v105, v105
	ds_write_b16 v167, v105 offset:4352
	v_cvt_pk_bf16_f32 v106, v106, v106
	ds_write_b16 v168, v106 offset:4352
	v_cvt_pk_bf16_f32 v107, v107, v107
	ds_write_b16 v169, v107 offset:4352
	v_cvt_pk_bf16_f32 v108, v108, v108
	ds_write_b16 v166, v108 offset:4480
	v_cvt_pk_bf16_f32 v109, v109, v109
	ds_write_b16 v167, v109 offset:4480
	v_cvt_pk_bf16_f32 v110, v110, v110
	ds_write_b16 v168, v110 offset:4480
	v_cvt_pk_bf16_f32 v111, v111, v111
	ds_write_b16 v169, v111 offset:4480
	v_cvt_pk_bf16_f32 v80, v80, v80
	ds_write_b16 v166, v80 offset:2048
	v_cvt_pk_bf16_f32 v81, v81, v81
	ds_write_b16 v167, v81 offset:2048
	v_cvt_pk_bf16_f32 v82, v82, v82
	ds_write_b16 v168, v82 offset:2048
	v_cvt_pk_bf16_f32 v83, v83, v83
	ds_write_b16 v169, v83 offset:2048
	v_cvt_pk_bf16_f32 v84, v84, v84
	ds_write_b16 v166, v84 offset:2176
	v_cvt_pk_bf16_f32 v85, v85, v85
	ds_write_b16 v167, v85 offset:2176
	v_cvt_pk_bf16_f32 v86, v86, v86
	ds_write_b16 v168, v86 offset:2176
	v_cvt_pk_bf16_f32 v87, v87, v87
	ds_write_b16 v169, v87 offset:2176
	v_cvt_pk_bf16_f32 v88, v88, v88
	ds_write_b16 v166, v88 offset:2304
	v_cvt_pk_bf16_f32 v89, v89, v89
	ds_write_b16 v167, v89 offset:2304
	v_cvt_pk_bf16_f32 v90, v90, v90
	ds_write_b16 v168, v90 offset:2304
	v_cvt_pk_bf16_f32 v91, v91, v91
	ds_write_b16 v169, v91 offset:2304
	v_cvt_pk_bf16_f32 v92, v92, v92
	ds_write_b16 v166, v92 offset:2432
	v_cvt_pk_bf16_f32 v93, v93, v93
	ds_write_b16 v167, v93 offset:2432
	v_cvt_pk_bf16_f32 v94, v94, v94
	ds_write_b16 v168, v94 offset:2432
	v_cvt_pk_bf16_f32 v95, v95, v95
	ds_write_b16 v169, v95 offset:2432
	v_cvt_pk_bf16_f32 v64, v64, v64
	ds_write_b16 v166, v64 offset:6144
	v_cvt_pk_bf16_f32 v65, v65, v65
	ds_write_b16 v167, v65 offset:6144
	v_cvt_pk_bf16_f32 v66, v66, v66
	ds_write_b16 v168, v66 offset:6144
	v_cvt_pk_bf16_f32 v67, v67, v67
	ds_write_b16 v169, v67 offset:6144
	v_cvt_pk_bf16_f32 v68, v68, v68
	ds_write_b16 v166, v68 offset:6272
	v_cvt_pk_bf16_f32 v69, v69, v69
	ds_write_b16 v167, v69 offset:6272
	v_cvt_pk_bf16_f32 v70, v70, v70
	ds_write_b16 v168, v70 offset:6272
	v_cvt_pk_bf16_f32 v71, v71, v71
	ds_write_b16 v169, v71 offset:6272
	v_cvt_pk_bf16_f32 v72, v72, v72
	ds_write_b16 v166, v72 offset:6400
	v_cvt_pk_bf16_f32 v73, v73, v73
	ds_write_b16 v167, v73 offset:6400
	v_cvt_pk_bf16_f32 v74, v74, v74
	ds_write_b16 v168, v74 offset:6400
	v_cvt_pk_bf16_f32 v75, v75, v75
	ds_write_b16 v169, v75 offset:6400
	v_cvt_pk_bf16_f32 v76, v76, v76
	ds_write_b16 v166, v76 offset:6528
	v_cvt_pk_bf16_f32 v77, v77, v77
	ds_write_b16 v167, v77 offset:6528
	v_cvt_pk_bf16_f32 v78, v78, v78
	ds_write_b16 v168, v78 offset:6528
	v_cvt_pk_bf16_f32 v79, v79, v79
	ds_write_b16 v169, v79 offset:6528
	v_cvt_pk_bf16_f32 v48, v48, v48
	ds_write_b16 v166, v48 offset:8192
	v_cvt_pk_bf16_f32 v49, v49, v49
	ds_write_b16 v167, v49 offset:8192
	v_cvt_pk_bf16_f32 v50, v50, v50
	ds_write_b16 v168, v50 offset:8192
	v_cvt_pk_bf16_f32 v51, v51, v51
	ds_write_b16 v169, v51 offset:8192
	v_cvt_pk_bf16_f32 v52, v52, v52
	ds_write_b16 v166, v52 offset:8320
	v_cvt_pk_bf16_f32 v53, v53, v53
	ds_write_b16 v167, v53 offset:8320
	v_cvt_pk_bf16_f32 v54, v54, v54
	ds_write_b16 v168, v54 offset:8320
	v_cvt_pk_bf16_f32 v55, v55, v55
	ds_write_b16 v169, v55 offset:8320
	v_cvt_pk_bf16_f32 v56, v56, v56
	ds_write_b16 v166, v56 offset:8448
	v_cvt_pk_bf16_f32 v57, v57, v57
	ds_write_b16 v167, v57 offset:8448
	v_cvt_pk_bf16_f32 v58, v58, v58
	ds_write_b16 v168, v58 offset:8448
	v_cvt_pk_bf16_f32 v59, v59, v59
	ds_write_b16 v169, v59 offset:8448
	v_cvt_pk_bf16_f32 v60, v60, v60
	ds_write_b16 v166, v60 offset:8576
	v_cvt_pk_bf16_f32 v61, v61, v61
	ds_write_b16 v167, v61 offset:8576
	v_cvt_pk_bf16_f32 v62, v62, v62
	ds_write_b16 v168, v62 offset:8576
	v_cvt_pk_bf16_f32 v63, v63, v63
	ds_write_b16 v169, v63 offset:8576
	v_cvt_pk_bf16_f32 v32, v32, v32
	ds_write_b16 v166, v32 offset:12288
	v_cvt_pk_bf16_f32 v33, v33, v33
	ds_write_b16 v167, v33 offset:12288
	v_cvt_pk_bf16_f32 v34, v34, v34
	ds_write_b16 v168, v34 offset:12288
	v_cvt_pk_bf16_f32 v35, v35, v35
	ds_write_b16 v169, v35 offset:12288
	v_cvt_pk_bf16_f32 v36, v36, v36
	ds_write_b16 v166, v36 offset:12416
	v_cvt_pk_bf16_f32 v37, v37, v37
	ds_write_b16 v167, v37 offset:12416
	v_cvt_pk_bf16_f32 v38, v38, v38
	ds_write_b16 v168, v38 offset:12416
	v_cvt_pk_bf16_f32 v39, v39, v39
	ds_write_b16 v169, v39 offset:12416
	v_cvt_pk_bf16_f32 v40, v40, v40
	ds_write_b16 v166, v40 offset:12544
	v_cvt_pk_bf16_f32 v41, v41, v41
	ds_write_b16 v167, v41 offset:12544
	v_cvt_pk_bf16_f32 v42, v42, v42
	ds_write_b16 v168, v42 offset:12544
	v_cvt_pk_bf16_f32 v43, v43, v43
	ds_write_b16 v169, v43 offset:12544
	v_cvt_pk_bf16_f32 v44, v44, v44
	ds_write_b16 v166, v44 offset:12672
	v_cvt_pk_bf16_f32 v45, v45, v45
	ds_write_b16 v167, v45 offset:12672
	v_cvt_pk_bf16_f32 v46, v46, v46
	ds_write_b16 v168, v46 offset:12672
	v_cvt_pk_bf16_f32 v47, v47, v47
	ds_write_b16 v169, v47 offset:12672
	v_cvt_pk_bf16_f32 v16, v16, v16
	ds_write_b16 v166, v16 offset:10240
	v_cvt_pk_bf16_f32 v17, v17, v17
	ds_write_b16 v167, v17 offset:10240
	v_cvt_pk_bf16_f32 v18, v18, v18
	ds_write_b16 v168, v18 offset:10240
	v_cvt_pk_bf16_f32 v19, v19, v19
	ds_write_b16 v169, v19 offset:10240
	v_cvt_pk_bf16_f32 v20, v20, v20
	ds_write_b16 v166, v20 offset:10368
	v_cvt_pk_bf16_f32 v21, v21, v21
	ds_write_b16 v167, v21 offset:10368
	v_cvt_pk_bf16_f32 v22, v22, v22
	ds_write_b16 v168, v22 offset:10368
	v_cvt_pk_bf16_f32 v23, v23, v23
	ds_write_b16 v169, v23 offset:10368
	v_cvt_pk_bf16_f32 v24, v24, v24
	ds_write_b16 v166, v24 offset:10496
	v_cvt_pk_bf16_f32 v25, v25, v25
	ds_write_b16 v167, v25 offset:10496
	v_cvt_pk_bf16_f32 v26, v26, v26
	ds_write_b16 v168, v26 offset:10496
	v_cvt_pk_bf16_f32 v27, v27, v27
	ds_write_b16 v169, v27 offset:10496
	v_cvt_pk_bf16_f32 v28, v28, v28
	ds_write_b16 v166, v28 offset:10624
	v_cvt_pk_bf16_f32 v29, v29, v29
	ds_write_b16 v167, v29 offset:10624
	v_cvt_pk_bf16_f32 v30, v30, v30
	ds_write_b16 v168, v30 offset:10624
	v_cvt_pk_bf16_f32 v31, v31, v31
	ds_write_b16 v169, v31 offset:10624
	v_cvt_pk_bf16_f32 v0, v0, v0
	ds_write_b16 v166, v0 offset:14336
	v_cvt_pk_bf16_f32 v1, v1, v1
	ds_write_b16 v167, v1 offset:14336
	v_cvt_pk_bf16_f32 v2, v2, v2
	ds_write_b16 v168, v2 offset:14336
	v_cvt_pk_bf16_f32 v3, v3, v3
	ds_write_b16 v169, v3 offset:14336
	v_cvt_pk_bf16_f32 v4, v4, v4
	ds_write_b16 v166, v4 offset:14464
	v_cvt_pk_bf16_f32 v5, v5, v5
	ds_write_b16 v167, v5 offset:14464
	v_cvt_pk_bf16_f32 v6, v6, v6
	ds_write_b16 v168, v6 offset:14464
	v_cvt_pk_bf16_f32 v7, v7, v7
	ds_write_b16 v169, v7 offset:14464
	v_cvt_pk_bf16_f32 v8, v8, v8
	ds_write_b16 v166, v8 offset:14592
	v_cvt_pk_bf16_f32 v9, v9, v9
	ds_write_b16 v167, v9 offset:14592
	v_cvt_pk_bf16_f32 v10, v10, v10
	ds_write_b16 v168, v10 offset:14592
	v_cvt_pk_bf16_f32 v11, v11, v11
	ds_write_b16 v169, v11 offset:14592
	v_cvt_pk_bf16_f32 v12, v12, v12
	ds_write_b16 v166, v12 offset:14720
	v_cvt_pk_bf16_f32 v13, v13, v13
	ds_write_b16 v167, v13 offset:14720
	v_cvt_pk_bf16_f32 v14, v14, v14
	ds_write_b16 v168, v14 offset:14720
	v_cvt_pk_bf16_f32 v15, v15, v15
	ds_write_b16 v169, v15 offset:14720
	s_waitcnt lgkmcnt(0)
	ds_read_b128 v[128:131], v170 offset:0
	ds_read_b128 v[132:135], v171 offset:1024
	ds_read_b128 v[136:139], v170 offset:2048
	ds_read_b128 v[140:143], v171 offset:3072
	s_waitcnt lgkmcnt(3)
	global_store_dwordx4 v[152:153], v[128:131], off
	s_waitcnt lgkmcnt(2)
	global_store_dwordx4 v[152:153], v[132:135], off offset:1024
	s_waitcnt lgkmcnt(1)
	global_store_dwordx4 v[152:153], v[136:139], off offset:2048
	s_waitcnt lgkmcnt(0)
	global_store_dwordx4 v[152:153], v[140:143], off offset:3072
	ds_read_b128 v[128:131], v170 offset:4096
	ds_read_b128 v[132:135], v171 offset:5120
	ds_read_b128 v[136:139], v170 offset:6144
	ds_read_b128 v[140:143], v171 offset:7168
	s_waitcnt lgkmcnt(3)
	global_store_dwordx4 v[154:155], v[128:131], off
	s_waitcnt lgkmcnt(2)
	global_store_dwordx4 v[154:155], v[132:135], off offset:1024
	s_waitcnt lgkmcnt(1)
	global_store_dwordx4 v[154:155], v[136:139], off offset:2048
	s_waitcnt lgkmcnt(0)
	global_store_dwordx4 v[154:155], v[140:143], off offset:3072
	ds_read_b128 v[128:131], v170 offset:8192
	ds_read_b128 v[132:135], v171 offset:9216
	ds_read_b128 v[136:139], v170 offset:10240
	ds_read_b128 v[140:143], v171 offset:11264
	s_waitcnt lgkmcnt(3)
	global_store_dwordx4 v[156:157], v[128:131], off
	s_waitcnt lgkmcnt(2)
	global_store_dwordx4 v[156:157], v[132:135], off offset:1024
	s_waitcnt lgkmcnt(1)
	global_store_dwordx4 v[156:157], v[136:139], off offset:2048
	s_waitcnt lgkmcnt(0)
	global_store_dwordx4 v[156:157], v[140:143], off offset:3072
	ds_read_b128 v[128:131], v170 offset:12288
	ds_read_b128 v[132:135], v171 offset:13312
	ds_read_b128 v[136:139], v170 offset:14336
	ds_read_b128 v[140:143], v171 offset:15360
	s_waitcnt lgkmcnt(3)
	global_store_dwordx4 v[158:159], v[128:131], off
	s_waitcnt lgkmcnt(2)
	global_store_dwordx4 v[158:159], v[132:135], off offset:1024
	s_waitcnt lgkmcnt(1)
	global_store_dwordx4 v[158:159], v[136:139], off offset:2048
	s_waitcnt lgkmcnt(0)
	global_store_dwordx4 v[158:159], v[140:143], off offset:3072
	s_barrier
	s_branch .LBB0_231
